# lever 8 variant: LDS read-ahead distance 10 (was 6) in the scan phases 7 and 14
# speedup vs baseline: 1.0107x; 1.0031x over previous
.LBB0_1046:
	v_mov_b32_e32 v37, v34
	v_mov_b32_e32 v34, v33
	v_mov_b32_e32 v36, v32
	v_pk_mul_f32 v[32:33], v[80:81], v[34:35]
	v_mov_b32_e32 v34, v38
	v_mov_b32_e32 v35, v40
	v_pk_mul_f32 v[36:37], v[80:81], v[36:37]
	v_pk_mul_f32 v[34:35], v[80:81], v[34:35]
	v_cvt_pk_bf16_f32 v36, v36, v37
	v_mov_b32_e32 v40, v39
	v_cvt_pk_bf16_f32 v37, v34, v35
	v_mov_b32_e32 v34, v42
	v_mov_b32_e32 v35, v44
	v_mov_b32_e32 v44, v43
	v_pk_mul_f32 v[38:39], v[80:81], v[40:41]
	v_pk_mul_f32 v[34:35], v[80:81], v[34:35]
	v_pk_mul_f32 v[40:41], v[80:81], v[44:45]
	v_cvt_pk_bf16_f32 v32, v32, v33
	v_cvt_pk_bf16_f32 v33, v38, v39
	v_cvt_pk_bf16_f32 v38, v34, v35
	v_cvt_pk_bf16_f32 v34, v40, v41
	v_mov_b32_e32 v40, v46
	v_mov_b32_e32 v41, v48
	v_pk_mul_f32 v[40:41], v[80:81], v[40:41]
	v_mov_b32_e32 v48, v47
	v_pk_mul_f32 v[42:43], v[80:81], v[48:49]
	v_cvt_pk_bf16_f32 v39, v40, v41
	v_mov_b32_e32 v40, v50
	v_mov_b32_e32 v41, v52
	v_mov_b32_e32 v52, v51
	v_cvt_pk_bf16_f32 v35, v42, v43
	v_pk_mul_f32 v[40:41], v[80:81], v[40:41]
	v_pk_mul_f32 v[42:43], v[80:81], v[52:53]
	v_cvt_pk_bf16_f32 v44, v40, v41
	v_cvt_pk_bf16_f32 v40, v42, v43
	v_mov_b32_e32 v42, v54
	v_mov_b32_e32 v43, v56
	v_pk_mul_f32 v[42:43], v[80:81], v[42:43]
	v_mov_b32_e32 v56, v55
	v_cvt_pk_bf16_f32 v45, v42, v43
	v_mov_b32_e32 v42, v58
	v_mov_b32_e32 v43, v60
	v_mov_b32_e32 v60, v59
	v_pk_mul_f32 v[46:47], v[80:81], v[56:57]
	v_pk_mul_f32 v[42:43], v[80:81], v[42:43]
	v_pk_mul_f32 v[48:49], v[80:81], v[60:61]
	v_cvt_pk_bf16_f32 v41, v46, v47
	v_cvt_pk_bf16_f32 v46, v42, v43
	v_cvt_pk_bf16_f32 v42, v48, v49
	v_mov_b32_e32 v48, v62
	v_mov_b32_e32 v49, v90
	v_mov_b32_e32 v90, v63
	v_pk_mul_f32 v[48:49], v[80:81], v[48:49]
	v_pk_mul_f32 v[50:51], v[80:81], v[90:91]
	v_cvt_pk_bf16_f32 v47, v48, v49
	v_cvt_pk_bf16_f32 v43, v50, v51
	s_waitcnt lgkmcnt(0)
	s_barrier
	s_waitcnt lgkmcnt(0)
	ds_read_b128 v[196:199], v97
	v_add_u32_e32 v52, v98, v100
	s_add_i32 s50, s50, -1
	s_add_i32 s54, s54, 1
	s_cmp_lg_u32 s50, -2
	s_waitcnt lgkmcnt(0)
	v_pk_mul_f32 v[48:49], v[4:5], v[196:197]
	v_pk_mul_f32 v[50:51], v[6:7], v[198:199]
	v_cvt_pk_bf16_f32 v48, v48, v49
	v_cvt_pk_bf16_f32 v49, v50, v51
	ds_write_b64 v52, v[48:49] offset:45056
	ds_read_b128 v[200:203], v97 offset:64
	s_waitcnt lgkmcnt(0)
	v_pk_mul_f32 v[48:49], v[0:1], v[200:201]
	v_pk_mul_f32 v[50:51], v[2:3], v[202:203]
	v_cvt_pk_bf16_f32 v48, v48, v49
	v_cvt_pk_bf16_f32 v49, v50, v51
	ds_write_b64 v123, v[48:49] offset:45056
	ds_read_b128 v[204:207], v97 offset:128
	s_waitcnt lgkmcnt(0)
	v_pk_mul_f32 v[48:49], v[8:9], v[204:205]
	v_pk_mul_f32 v[50:51], v[10:11], v[206:207]
	v_cvt_pk_bf16_f32 v48, v48, v49
	v_cvt_pk_bf16_f32 v49, v50, v51
	ds_write_b64 v124, v[48:49] offset:45056
	ds_read_b128 v[208:211], v97 offset:192
	s_waitcnt lgkmcnt(0)
	v_pk_mul_f32 v[48:49], v[12:13], v[208:209]
	v_pk_mul_f32 v[50:51], v[14:15], v[210:211]
	v_cvt_pk_bf16_f32 v48, v48, v49
	v_cvt_pk_bf16_f32 v49, v50, v51
	ds_write_b64 v125, v[48:49] offset:45056
	ds_read_b128 v[212:215], v97 offset:256
	s_waitcnt lgkmcnt(0)
	v_pk_mul_f32 v[48:49], v[16:17], v[212:213]
	v_pk_mul_f32 v[50:51], v[18:19], v[214:215]
	v_cvt_pk_bf16_f32 v48, v48, v49
	v_cvt_pk_bf16_f32 v49, v50, v51
	ds_write_b64 v52, v[48:49] offset:45184
	ds_read_b128 v[216:219], v97 offset:320
	s_waitcnt lgkmcnt(0)
	v_pk_mul_f32 v[48:49], v[20:21], v[216:217]
	v_pk_mul_f32 v[50:51], v[22:23], v[218:219]
	v_cvt_pk_bf16_f32 v48, v48, v49
	v_cvt_pk_bf16_f32 v49, v50, v51
	ds_write_b64 v52, v[48:49] offset:45216
	ds_read_b128 v[220:223], v97 offset:384
	s_waitcnt lgkmcnt(0)
	v_pk_mul_f32 v[48:49], v[24:25], v[220:221]
	v_pk_mul_f32 v[50:51], v[26:27], v[222:223]
	v_cvt_pk_bf16_f32 v48, v48, v49
	v_cvt_pk_bf16_f32 v49, v50, v51
	ds_write_b64 v52, v[48:49] offset:45248
	ds_read_b128 v[224:227], v97 offset:448
	s_waitcnt lgkmcnt(0)
	v_pk_mul_f32 v[48:49], v[28:29], v[224:225]
	v_pk_mul_f32 v[50:51], v[30:31], v[226:227]
	v_cvt_pk_bf16_f32 v48, v48, v49
	v_cvt_pk_bf16_f32 v49, v50, v51
	ds_write_b64 v52, v[48:49] offset:45280
	ds_read_b128 v[228:231], v126 offset:17408
	ds_read_b128 v[232:235], v126 offset:17472
	ds_read_b128 v[236:239], v126 offset:17536
	ds_read_b128 v[244:247], v126 offset:17600
	ds_read_b128 v[248:251], v126 offset:21824
	ds_read_b128 v[252:255], v126 offset:21760
	ds_read_b128 v[196:199], v126 offset:21888
	ds_read_b128 v[200:203], v126 offset:21952
	ds_read_b128 v[204:207], v126 offset:26176
	ds_read_b128 v[208:211], v126 offset:26112
	v_add_u32_e32 v48, v98, v96
	ds_read_b128 v[60:63], v48
	ds_read_b128 v[52:55], v48 offset:64
	ds_read_b128 v[56:59], v48 offset:128
	ds_read_b128 v[48:51], v48 offset:192
	s_waitcnt lgkmcnt(3)
	v_mfma_f32_16x16x32_bf16 v[172:175], v[228:231], v[60:63], 0
	ds_read_b128 v[212:215], v126 offset:26240
	s_waitcnt lgkmcnt(3)
	v_mfma_f32_16x16x32_bf16 v[172:175], v[232:235], v[52:55], v[172:175]
	ds_read_b128 v[216:219], v126 offset:26304
	s_waitcnt lgkmcnt(3)
	v_mfma_f32_16x16x32_bf16 v[172:175], v[236:239], v[56:59], v[172:175]
	ds_read_b128 v[220:223], v126 offset:30528
	s_waitcnt lgkmcnt(3)
	v_mfma_f32_16x16x32_bf16 v[172:175], v[244:247], v[48:51], v[172:175]
	ds_read_b128 v[224:227], v126 offset:30464
	s_nop 6
	v_cndmask_b32_e64 v64, v172, 0, s[2:3]
	v_cndmask_b32_e64 v77, v173, 0, s[4:5]
	v_cndmask_b32_e64 v89, v174, 0, s[6:7]
	v_cndmask_b32_e64 v91, v175, 0, s[8:9]
	v_mfma_f32_16x16x32_bf16 v[172:175], v[252:255], v[60:63], 0
	ds_read_b128 v[228:231], v126 offset:30592
	v_cvt_pk_bf16_f32 v90, v64, v77
	v_cvt_pk_bf16_f32 v91, v89, v91
	v_mfma_f32_16x16x32_bf16 v[172:175], v[248:251], v[52:55], v[172:175]
	v_mfma_f32_16x16x32_bf16 v[172:175], v[196:199], v[56:59], v[172:175]
	v_mfma_f32_16x16x32_bf16 v[172:175], v[200:203], v[48:51], v[172:175]
	s_nop 6
	s_nop 0
	v_cndmask_b32_e64 v64, v172, 0, s[10:11]
	v_cndmask_b32_e64 v89, v174, 0, s[14:15]
	v_cndmask_b32_e64 v172, v175, 0, s[16:17]
	v_cndmask_b32_e64 v77, v173, 0, s[12:13]
	v_cvt_pk_bf16_f32 v177, v89, v172
	v_mfma_f32_16x16x32_bf16 v[172:175], v[208:211], v[60:63], 0
	v_cvt_pk_bf16_f32 v176, v64, v77
	v_mfma_f32_16x16x32_bf16 v[172:175], v[204:207], v[52:55], v[172:175]
	s_waitcnt lgkmcnt(4)
	v_mfma_f32_16x16x32_bf16 v[172:175], v[212:215], v[56:59], v[172:175]
	s_waitcnt lgkmcnt(3)
	v_mfma_f32_16x16x32_bf16 v[172:175], v[216:219], v[48:51], v[172:175]
	s_nop 6
	s_nop 0
	v_cndmask_b32_e64 v64, v172, 0, s[18:19]
	v_cndmask_b32_e64 v89, v174, 0, s[22:23]
	v_cndmask_b32_e64 v172, v175, 0, s[24:25]
	v_cndmask_b32_e64 v77, v173, 0, s[20:21]
	v_cvt_pk_bf16_f32 v193, v89, v172
	s_waitcnt lgkmcnt(1)
	v_mfma_f32_16x16x32_bf16 v[172:175], v[224:227], v[60:63], 0
	v_cvt_pk_bf16_f32 v192, v64, v77
	v_mfma_f32_16x16x32_bf16 v[172:175], v[220:223], v[52:55], v[172:175]
	s_waitcnt lgkmcnt(0)
	v_mfma_f32_16x16x32_bf16 v[172:175], v[228:231], v[56:59], v[172:175]
	ds_read_b128 v[188:191], v126 offset:30656
	s_waitcnt lgkmcnt(0)
	s_barrier
	v_mfma_f32_16x16x32_bf16 v[172:175], v[188:191], v[48:51], v[172:175]
	s_nop 7
	v_cndmask_b32_e64 v64, v172, 0, s[26:27]
	v_cndmask_b32_e64 v77, v173, 0, s[28:29]
	v_cvt_pk_bf16_f32 v172, v64, v77
	v_add_u32_e32 v64, v99, v100
	v_cndmask_b32_e64 v89, v174, 0, s[30:31]
	v_cndmask_b32_e64 v173, v175, 0, s[34:35]
	v_add_u32_e32 v64, 0xf000, v64
	v_cvt_pk_bf16_f32 v173, v89, v173
	ds_write2_b64 v64, v[90:91], v[176:177] offset0:128 offset1:132
	ds_write2_b64 v64, v[192:193], v[172:173] offset0:136 offset1:140
	ds_write_b128 v127, v[36:39] offset:17408
	ds_write_b128 v127, v[44:47] offset:17424
	ds_write_b128 v127, v[32:35] offset:17552
	ds_write_b128 v127, v[40:43] offset:17568
	v_ashrrev_i32_e32 v40, 8, v147
	v_cmp_gt_i32_e32 vcc, 32, v40
	v_lshlrev_b32_e32 v40, 1, v40
	v_subrev_u32_e32 v42, 63, v40
	v_or_b32_e32 v40, 1, v40
	v_ashrrev_i32_e32 v41, 31, v40
	v_cndmask_b32_e32 v41, 0, v41, vcc
	v_cndmask_b32_e32 v40, v42, v40, vcc
	v_cndmask_b32_e32 v64, v133, v134, vcc
	v_lshl_add_u64 v[42:43], s[94:95], 0, v[64:65]
	v_lshlrev_b64 v[40:41], 20, v[40:41]
	v_add_u32_e32 v46, v99, v96
	v_lshl_add_u64 v[40:41], v[42:43], 0, v[40:41]
	v_and_b32_e32 v42, 0x7f800, v148
	s_waitcnt lgkmcnt(0)
	s_barrier
	s_waitcnt lgkmcnt(0)
	ds_read_b128 v[196:199], v46 offset:62464
	ds_read_b128 v[200:203], v46 offset:62528
	ds_read_b128 v[204:207], v128 offset:35840
	ds_read_b128 v[208:211], v128 offset:35904
	ds_read_b128 v[212:215], v126 offset:45056
	ds_read_b128 v[216:219], v126 offset:45120
	ds_read_b128 v[220:223], v126 offset:45184
	ds_read_b128 v[224:227], v126 offset:45248
	ds_read_b128 v[228:231], v128 offset:38208
	ds_read_b128 v[232:235], v128 offset:38144
	v_lshlrev_b32_e32 v64, 1, v42
	s_waitcnt lgkmcnt(7)
	v_mfma_f32_16x16x32_bf16 v[42:45], v[204:207], v[196:199], 0
	ds_read_b128 v[236:239], v126 offset:49408
	ds_read_b128 v[244:247], v126 offset:49472
	v_lshl_add_u64 v[40:41], v[40:41], 0, v[64:65]
	v_mov_b32_e32 v89, v65
	v_lshl_add_u64 v[40:41], v[40:41], 0, v[88:89]
	s_waitcnt lgkmcnt(8)
	v_mfma_f32_16x16x32_bf16 v[42:45], v[208:211], v[200:203], v[42:45]
	ds_read_b128 v[248:251], v126 offset:49536
	ds_read_b128 v[252:255], v126 offset:49600
	v_lshl_add_u64 v[40:41], v[78:79], 1, v[40:41]
	v_mov_b32_e32 v77, v65
	s_waitcnt lgkmcnt(9)
	v_mfma_f32_16x16x32_bf16 v[42:45], v[212:215], v[60:63], v[42:45]
	ds_read_b128 v[204:207], v128 offset:40512
	v_lshl_add_u64 v[40:41], v[40:41], 0, v[76:77]
	v_add_u32_e32 v148, 0xfffe0000, v148
	s_waitcnt lgkmcnt(9)
	v_mfma_f32_16x16x32_bf16 v[42:45], v[216:219], v[52:55], v[42:45]
	ds_read_b128 v[208:211], v128 offset:40448
	v_subrev_u32_e32 v147, 64, v147
	s_waitcnt lgkmcnt(9)
	v_mfma_f32_16x16x32_bf16 v[42:45], v[220:223], v[56:59], v[42:45]
	ds_read_b128 v[212:215], v126 offset:53760
	s_waitcnt lgkmcnt(9)
	v_mfma_f32_16x16x32_bf16 v[42:45], v[224:227], v[48:51], v[42:45]
	ds_read_b128 v[216:219], v126 offset:53824
	s_nop 6
	v_cvt_pk_bf16_f32 v42, v42, v43
	v_cvt_pk_bf16_f32 v43, v44, v45
	global_store_dwordx2 v[40:41], v[42:43], off
	s_waitcnt lgkmcnt(8)
	v_mfma_f32_16x16x32_bf16 v[42:45], v[232:235], v[196:199], 0
	ds_read_b128 v[220:223], v126 offset:53888
	v_mfma_f32_16x16x32_bf16 v[42:45], v[228:231], v[200:203], v[42:45]
	ds_read_b128 v[224:227], v128 offset:42752
	s_waitcnt lgkmcnt(9)
	v_mfma_f32_16x16x32_bf16 v[42:45], v[236:239], v[60:63], v[42:45]
	ds_read_b128 v[232:235], v126 offset:58112
	s_waitcnt lgkmcnt(9)
	v_mfma_f32_16x16x32_bf16 v[42:45], v[244:247], v[52:55], v[42:45]
	ds_read_b128 v[228:231], v126 offset:58176
	s_waitcnt lgkmcnt(9)
	v_mfma_f32_16x16x32_bf16 v[42:45], v[248:251], v[56:59], v[42:45]
	ds_read_b128 v[236:239], v126 offset:58240
	s_waitcnt lgkmcnt(9)
	v_mfma_f32_16x16x32_bf16 v[42:45], v[252:255], v[48:51], v[42:45]
	ds_read_b128 v[244:247], v126 offset:58304
	s_nop 6
	v_cvt_pk_bf16_f32 v42, v42, v43
	v_cvt_pk_bf16_f32 v43, v44, v45
	global_store_dwordx2 v[40:41], v[42:43], off offset:32
	s_waitcnt lgkmcnt(8)
	v_mfma_f32_16x16x32_bf16 v[42:45], v[208:211], v[196:199], 0
	ds_read_b128 v[248:251], v101
	v_mfma_f32_16x16x32_bf16 v[42:45], v[204:207], v[200:203], v[42:45]
	ds_read_b128 v[252:255], v128 offset:17408
	s_waitcnt lgkmcnt(9)
	v_mfma_f32_16x16x32_bf16 v[42:45], v[212:215], v[60:63], v[42:45]
	ds_read_b128 v[208:211], v128 offset:17472
	s_waitcnt lgkmcnt(9)
	v_mfma_f32_16x16x32_bf16 v[42:45], v[216:219], v[52:55], v[42:45]
	ds_read_b128 v[204:207], v101 offset:64
	s_waitcnt lgkmcnt(9)
	v_mfma_f32_16x16x32_bf16 v[42:45], v[220:223], v[56:59], v[42:45]
	ds_read_b128 v[212:215], v128 offset:19712
	ds_read_b128 v[172:175], v126 offset:53952
	s_waitcnt lgkmcnt(0)
	v_mfma_f32_16x16x32_bf16 v[42:45], v[172:175], v[48:51], v[42:45]
	s_nop 7
	v_cvt_pk_bf16_f32 v42, v42, v43
	v_cvt_pk_bf16_f32 v43, v44, v45
	global_store_dwordx2 v[40:41], v[42:43], off offset:64
	v_mfma_f32_16x16x32_bf16 v[36:39], v[224:227], v[196:199], 0
	ds_read_b128 v[216:219], v128 offset:19776
	ds_read_b128 v[42:45], v128 offset:42816
	s_waitcnt lgkmcnt(0)
	v_mfma_f32_16x16x32_bf16 v[32:35], v[42:45], v[200:203], v[36:39]
	s_nop 4
	v_mfma_f32_16x16x32_bf16 v[32:35], v[232:235], v[60:63], v[32:35]
	ds_read_b128 v[220:223], v101 offset:128
	v_mfma_f32_16x16x32_bf16 v[32:35], v[228:231], v[52:55], v[32:35]
	ds_read_b128 v[196:199], v128 offset:22016
	v_mfma_f32_16x16x32_bf16 v[32:35], v[236:239], v[56:59], v[32:35]
	ds_read_b128 v[224:227], v128 offset:22080
	v_mfma_f32_16x16x32_bf16 v[32:35], v[244:247], v[48:51], v[32:35]
	ds_read_b128 v[200:203], v101 offset:192
	s_nop 7
	v_cvt_pk_bf16_f32 v32, v32, v33
	v_cvt_pk_bf16_f32 v33, v34, v35
	global_store_dwordx2 v[40:41], v[32:33], off offset:96
	ds_read_b128 v[36:39], v46 offset:35840
	ds_read_b128 v[32:35], v46 offset:35904
	v_pk_mul_f32 v[4:5], v[4:5], v[248:249]
	ds_read_b128 v[232:235], v128 offset:24320
	v_pk_mul_f32 v[6:7], v[6:7], v[250:251]
	s_waitcnt lgkmcnt(2)
	s_nop 0
	v_mfma_f32_16x16x32_bf16 v[4:7], v[252:255], v[36:39], v[4:7]
	ds_read_b128 v[228:231], v128 offset:24384
	s_waitcnt lgkmcnt(2)
	v_mfma_f32_16x16x32_bf16 v[4:7], v[208:211], v[32:35], v[4:7]
	ds_read_b128 v[236:239], v101 offset:256
	v_pk_mul_f32 v[0:1], v[0:1], v[204:205]
	ds_read_b128 v[244:247], v128 offset:26624
	v_pk_mul_f32 v[2:3], v[2:3], v[206:207]
	s_nop 1
	v_mfma_f32_16x16x32_bf16 v[0:3], v[212:215], v[36:39], v[0:3]
	ds_read_b128 v[248:251], v128 offset:26688
	v_mfma_f32_16x16x32_bf16 v[0:3], v[216:219], v[32:35], v[0:3]
	ds_read_b128 v[252:255], v101 offset:320
	v_pk_mul_f32 v[8:9], v[8:9], v[220:221]
	ds_read_b128 v[208:211], v128 offset:28928
	v_pk_mul_f32 v[10:11], v[10:11], v[222:223]
	s_nop 1
	v_mfma_f32_16x16x32_bf16 v[8:11], v[196:199], v[36:39], v[8:11]
	ds_read_b128 v[204:207], v128 offset:28992
	v_mfma_f32_16x16x32_bf16 v[8:11], v[224:227], v[32:35], v[8:11]
	ds_read_b128 v[212:215], v101 offset:384
	v_pk_mul_f32 v[12:13], v[12:13], v[200:201]
	ds_read_b128 v[216:219], v128 offset:31232
	v_pk_mul_f32 v[14:15], v[14:15], v[202:203]
	s_waitcnt lgkmcnt(9)
	s_nop 0
	v_mfma_f32_16x16x32_bf16 v[12:15], v[232:235], v[36:39], v[12:15]
	ds_read_b128 v[220:223], v128 offset:31296
	s_waitcnt lgkmcnt(9)
	v_mfma_f32_16x16x32_bf16 v[12:15], v[228:231], v[32:35], v[12:15]
	ds_read_b128 v[196:199], v101 offset:448
	s_waitcnt lgkmcnt(9)
	v_pk_mul_f32 v[16:17], v[16:17], v[236:237]
	v_pk_mul_f32 v[18:19], v[18:19], v[238:239]
	s_waitcnt lgkmcnt(8)
	s_nop 0
	v_mfma_f32_16x16x32_bf16 v[16:19], v[244:247], v[36:39], v[16:19]
	s_waitcnt lgkmcnt(7)
	v_mfma_f32_16x16x32_bf16 v[16:19], v[248:251], v[32:35], v[16:19]
	s_waitcnt lgkmcnt(6)
	v_pk_mul_f32 v[20:21], v[20:21], v[252:253]
	v_pk_mul_f32 v[22:23], v[22:23], v[254:255]
	s_waitcnt lgkmcnt(5)
	s_nop 0
	v_mfma_f32_16x16x32_bf16 v[20:23], v[208:211], v[36:39], v[20:23]
	s_waitcnt lgkmcnt(4)
	v_mfma_f32_16x16x32_bf16 v[20:23], v[204:207], v[32:35], v[20:23]
	s_waitcnt lgkmcnt(3)
	v_pk_mul_f32 v[24:25], v[24:25], v[212:213]
	v_pk_mul_f32 v[26:27], v[26:27], v[214:215]
	s_waitcnt lgkmcnt(2)
	s_nop 0
	v_mfma_f32_16x16x32_bf16 v[24:27], v[216:219], v[36:39], v[24:27]
	s_waitcnt lgkmcnt(1)
	v_mfma_f32_16x16x32_bf16 v[24:27], v[220:223], v[32:35], v[24:27]
	s_waitcnt lgkmcnt(0)
	v_pk_mul_f32 v[28:29], v[28:29], v[196:197]
	v_pk_mul_f32 v[30:31], v[30:31], v[198:199]
	ds_read_b128 v[40:43], v128 offset:33536
	s_waitcnt lgkmcnt(0)
	v_mfma_f32_16x16x32_bf16 v[28:31], v[40:43], v[36:39], v[28:31]
	ds_read_b128 v[36:39], v128 offset:33600
	s_waitcnt lgkmcnt(0)
	s_barrier
	v_mfma_f32_16x16x32_bf16 v[28:31], v[36:39], v[32:35], v[28:31]
	s_cbranch_scc0 .LBB0_1040

.LBB0_1058:
	v_mov_b32_e32 v37, v34
	v_mov_b32_e32 v34, v33
	v_mov_b32_e32 v36, v32
	v_pk_mul_f32 v[32:33], v[76:77], v[34:35]
	v_mov_b32_e32 v34, v38
	v_mov_b32_e32 v35, v40
	v_pk_mul_f32 v[36:37], v[76:77], v[36:37]
	v_pk_mul_f32 v[34:35], v[76:77], v[34:35]
	v_cvt_pk_bf16_f32 v36, v36, v37
	v_mov_b32_e32 v40, v39
	v_cvt_pk_bf16_f32 v37, v34, v35
	v_mov_b32_e32 v34, v42
	v_mov_b32_e32 v35, v44
	v_mov_b32_e32 v44, v43
	v_pk_mul_f32 v[38:39], v[76:77], v[40:41]
	v_pk_mul_f32 v[34:35], v[76:77], v[34:35]
	v_pk_mul_f32 v[40:41], v[76:77], v[44:45]
	v_cvt_pk_bf16_f32 v32, v32, v33
	v_cvt_pk_bf16_f32 v33, v38, v39
	v_cvt_pk_bf16_f32 v38, v34, v35
	v_cvt_pk_bf16_f32 v34, v40, v41
	v_mov_b32_e32 v40, v46
	v_mov_b32_e32 v41, v48
	v_pk_mul_f32 v[40:41], v[76:77], v[40:41]
	v_mov_b32_e32 v48, v47
	v_pk_mul_f32 v[42:43], v[76:77], v[48:49]
	v_cvt_pk_bf16_f32 v39, v40, v41
	v_mov_b32_e32 v40, v50
	v_mov_b32_e32 v41, v52
	v_mov_b32_e32 v52, v51
	v_cvt_pk_bf16_f32 v35, v42, v43
	v_pk_mul_f32 v[40:41], v[76:77], v[40:41]
	v_pk_mul_f32 v[42:43], v[76:77], v[52:53]
	v_cvt_pk_bf16_f32 v44, v40, v41
	v_cvt_pk_bf16_f32 v40, v42, v43
	v_mov_b32_e32 v42, v54
	v_mov_b32_e32 v43, v56
	v_pk_mul_f32 v[42:43], v[76:77], v[42:43]
	v_mov_b32_e32 v56, v55
	v_cvt_pk_bf16_f32 v45, v42, v43
	v_mov_b32_e32 v42, v58
	v_mov_b32_e32 v43, v60
	v_mov_b32_e32 v60, v59
	v_pk_mul_f32 v[46:47], v[76:77], v[56:57]
	v_pk_mul_f32 v[42:43], v[76:77], v[42:43]
	v_pk_mul_f32 v[48:49], v[76:77], v[60:61]
	v_cvt_pk_bf16_f32 v41, v46, v47
	v_cvt_pk_bf16_f32 v46, v42, v43
	v_cvt_pk_bf16_f32 v42, v48, v49
	v_mov_b32_e32 v48, v62
	v_mov_b32_e32 v49, v86
	v_mov_b32_e32 v86, v63
	v_pk_mul_f32 v[48:49], v[76:77], v[48:49]
	v_pk_mul_f32 v[50:51], v[76:77], v[86:87]
	v_cvt_pk_bf16_f32 v47, v48, v49
	v_cvt_pk_bf16_f32 v43, v50, v51
	s_waitcnt lgkmcnt(0)
	s_barrier
	s_waitcnt lgkmcnt(0)
	ds_read_b128 v[196:199], v93
	v_add_u32_e32 v52, v94, v96
	v_add_u32_e32 v60, v94, v91
	s_add_i32 s52, s52, 1
	v_lshl_add_u64 v[78:79], v[78:79], 0, s[48:49]
	s_waitcnt lgkmcnt(0)
	v_pk_mul_f32 v[48:49], v[4:5], v[196:197]
	v_pk_mul_f32 v[50:51], v[6:7], v[198:199]
	v_cvt_pk_bf16_f32 v48, v48, v49
	v_cvt_pk_bf16_f32 v49, v50, v51
	ds_write_b64 v52, v[48:49] offset:45056
	ds_read_b128 v[200:203], v93 offset:64
	v_lshl_add_u64 v[80:81], v[80:81], 0, s[48:49]
	v_lshl_add_u64 v[82:83], v[82:83], 0, s[50:51]
	s_cmp_lg_u32 s52, 32
	s_waitcnt lgkmcnt(0)
	v_pk_mul_f32 v[48:49], v[0:1], v[200:201]
	v_pk_mul_f32 v[50:51], v[2:3], v[202:203]
	v_cvt_pk_bf16_f32 v48, v48, v49
	v_cvt_pk_bf16_f32 v49, v50, v51
	ds_write_b64 v118, v[48:49] offset:45056
	ds_read_b128 v[204:207], v93 offset:128
	s_waitcnt lgkmcnt(0)
	v_pk_mul_f32 v[48:49], v[8:9], v[204:205]
	v_pk_mul_f32 v[50:51], v[10:11], v[206:207]
	v_cvt_pk_bf16_f32 v48, v48, v49
	v_cvt_pk_bf16_f32 v49, v50, v51
	ds_write_b64 v119, v[48:49] offset:45056
	ds_read_b128 v[208:211], v93 offset:192
	s_waitcnt lgkmcnt(0)
	v_pk_mul_f32 v[48:49], v[12:13], v[208:209]
	v_pk_mul_f32 v[50:51], v[14:15], v[210:211]
	v_cvt_pk_bf16_f32 v48, v48, v49
	v_cvt_pk_bf16_f32 v49, v50, v51
	ds_write_b64 v120, v[48:49] offset:45056
	ds_read_b128 v[212:215], v93 offset:256
	s_waitcnt lgkmcnt(0)
	v_pk_mul_f32 v[48:49], v[16:17], v[212:213]
	v_pk_mul_f32 v[50:51], v[18:19], v[214:215]
	v_cvt_pk_bf16_f32 v48, v48, v49
	v_cvt_pk_bf16_f32 v49, v50, v51
	ds_write_b64 v52, v[48:49] offset:45184
	ds_read_b128 v[216:219], v93 offset:320
	s_waitcnt lgkmcnt(0)
	v_pk_mul_f32 v[48:49], v[20:21], v[216:217]
	v_pk_mul_f32 v[50:51], v[22:23], v[218:219]
	v_cvt_pk_bf16_f32 v48, v48, v49
	v_cvt_pk_bf16_f32 v49, v50, v51
	ds_write_b64 v52, v[48:49] offset:45216
	ds_read_b128 v[220:223], v93 offset:384
	s_waitcnt lgkmcnt(0)
	v_pk_mul_f32 v[48:49], v[24:25], v[220:221]
	v_pk_mul_f32 v[50:51], v[26:27], v[222:223]
	v_cvt_pk_bf16_f32 v48, v48, v49
	v_cvt_pk_bf16_f32 v49, v50, v51
	ds_write_b64 v52, v[48:49] offset:45248
	ds_read_b128 v[224:227], v93 offset:448
	s_waitcnt lgkmcnt(0)
	v_pk_mul_f32 v[48:49], v[28:29], v[224:225]
	v_pk_mul_f32 v[50:51], v[30:31], v[226:227]
	v_cvt_pk_bf16_f32 v48, v48, v49
	v_cvt_pk_bf16_f32 v49, v50, v51
	ds_write_b64 v52, v[48:49] offset:45280
	ds_read_b128 v[228:231], v121 offset:17408
	ds_read_b128 v[232:235], v121 offset:17472
	ds_read_b128 v[236:239], v121 offset:17536
	ds_read_b128 v[244:247], v121 offset:17600
	ds_read_b128 v[248:251], v121 offset:21824
	ds_read_b128 v[252:255], v121 offset:21760
	ds_read_b128 v[196:199], v121 offset:21888
	ds_read_b128 v[200:203], v121 offset:21952
	ds_read_b128 v[204:207], v121 offset:26176
	ds_read_b128 v[208:211], v121 offset:26112
	ds_read_b128 v[48:51], v60
	ds_read_b128 v[52:55], v60 offset:64
	ds_read_b128 v[56:59], v60 offset:128
	ds_read_b128 v[60:63], v60 offset:192
	s_waitcnt lgkmcnt(3)
	v_mfma_f32_16x16x32_bf16 v[164:167], v[228:231], v[48:51], 0
	ds_read_b128 v[212:215], v121 offset:26240
	s_waitcnt lgkmcnt(3)
	v_mfma_f32_16x16x32_bf16 v[164:167], v[232:235], v[52:55], v[164:167]
	ds_read_b128 v[216:219], v121 offset:26304
	s_waitcnt lgkmcnt(3)
	v_mfma_f32_16x16x32_bf16 v[164:167], v[236:239], v[56:59], v[164:167]
	ds_read_b128 v[220:223], v121 offset:30528
	s_waitcnt lgkmcnt(3)
	v_mfma_f32_16x16x32_bf16 v[164:167], v[244:247], v[60:63], v[164:167]
	ds_read_b128 v[224:227], v121 offset:30464
	s_nop 6
	v_cndmask_b32_e64 v86, v164, 0, s[0:1]
	v_cndmask_b32_e64 v87, 0, v165, s[2:3]
	v_cndmask_b32_e64 v163, v166, 0, s[4:5]
	v_cndmask_b32_e64 v164, v167, 0, s[6:7]
	v_cvt_pk_bf16_f32 v86, v86, v87
	v_cvt_pk_bf16_f32 v87, v163, v164
	v_mfma_f32_16x16x32_bf16 v[164:167], v[252:255], v[48:51], 0
	ds_read_b128 v[228:231], v121 offset:30592
	v_mfma_f32_16x16x32_bf16 v[164:167], v[248:251], v[52:55], v[164:167]
	v_mfma_f32_16x16x32_bf16 v[164:167], v[196:199], v[56:59], v[164:167]
	v_mfma_f32_16x16x32_bf16 v[164:167], v[200:203], v[60:63], v[164:167]
	s_nop 6
	s_nop 0
	v_cndmask_b32_e64 v163, v164, 0, s[8:9]
	v_cndmask_b32_e64 v164, v165, 0, s[10:11]
	v_cndmask_b32_e64 v165, v166, 0, s[12:13]
	v_cndmask_b32_e64 v166, v167, 0, s[14:15]
	v_cvt_pk_bf16_f32 v172, v163, v164
	v_cvt_pk_bf16_f32 v173, v165, v166
	v_mfma_f32_16x16x32_bf16 v[164:167], v[208:211], v[48:51], 0
	v_mfma_f32_16x16x32_bf16 v[164:167], v[204:207], v[52:55], v[164:167]
	s_waitcnt lgkmcnt(4)
	v_mfma_f32_16x16x32_bf16 v[164:167], v[212:215], v[56:59], v[164:167]
	s_waitcnt lgkmcnt(3)
	v_mfma_f32_16x16x32_bf16 v[164:167], v[216:219], v[60:63], v[164:167]
	s_nop 6
	s_nop 0
	v_cndmask_b32_e64 v163, v164, 0, s[16:17]
	v_cndmask_b32_e64 v164, v165, 0, s[18:19]
	v_cndmask_b32_e64 v165, v166, 0, s[20:21]
	v_cndmask_b32_e64 v166, v167, 0, s[22:23]
	v_cvt_pk_bf16_f32 v174, v163, v164
	v_cvt_pk_bf16_f32 v175, v165, v166
	s_waitcnt lgkmcnt(1)
	v_mfma_f32_16x16x32_bf16 v[164:167], v[224:227], v[48:51], 0
	v_mfma_f32_16x16x32_bf16 v[164:167], v[220:223], v[52:55], v[164:167]
	s_waitcnt lgkmcnt(0)
	v_mfma_f32_16x16x32_bf16 v[164:167], v[228:231], v[56:59], v[164:167]
	ds_read_b128 v[168:171], v121 offset:30656
	s_waitcnt lgkmcnt(0)
	s_barrier
	v_mfma_f32_16x16x32_bf16 v[164:167], v[168:171], v[60:63], v[164:167]
	s_nop 7
	v_cndmask_b32_e64 v163, v164, 0, s[24:25]
	v_cndmask_b32_e64 v164, v165, 0, s[26:27]
	v_cvt_pk_bf16_f32 v164, v163, v164
	v_add_u32_e32 v163, v95, v96
	v_cndmask_b32_e64 v165, v166, 0, s[28:29]
	v_cndmask_b32_e64 v166, v167, 0, s[30:31]
	v_add_u32_e32 v163, 0xf000, v163
	v_cvt_pk_bf16_f32 v165, v165, v166
	ds_write2_b64 v163, v[86:87], v[172:173] offset0:128 offset1:132
	ds_write2_b64 v163, v[174:175], v[164:165] offset0:136 offset1:140
	ds_write_b128 v122, v[36:39] offset:17408
	ds_write_b128 v122, v[44:47] offset:17424
	ds_write_b128 v122, v[32:35] offset:17552
	ds_write_b128 v122, v[40:43] offset:17568
	v_add_u32_e32 v86, v95, v91
	s_waitcnt lgkmcnt(0)
	s_barrier
	s_waitcnt lgkmcnt(0)
	ds_read_b128 v[196:199], v86 offset:62464
	ds_read_b128 v[200:203], v86 offset:62528
	ds_read_b128 v[204:207], v123 offset:35840
	ds_read_b128 v[208:211], v123 offset:35904
	ds_read_b128 v[212:215], v121 offset:45056
	ds_read_b128 v[216:219], v121 offset:45120
	ds_read_b128 v[220:223], v121 offset:45184
	ds_read_b128 v[224:227], v121 offset:45248
	ds_read_b128 v[228:231], v123 offset:38208
	ds_read_b128 v[232:235], v123 offset:38144
	s_waitcnt lgkmcnt(7)
	v_mfma_f32_16x16x32_bf16 v[40:43], v[204:207], v[196:199], 0
	ds_read_b128 v[236:239], v121 offset:49408
	ds_read_b128 v[244:247], v121 offset:49472
	s_waitcnt lgkmcnt(8)
	v_mfma_f32_16x16x32_bf16 v[40:43], v[208:211], v[200:203], v[40:43]
	ds_read_b128 v[248:251], v121 offset:49536
	ds_read_b128 v[252:255], v121 offset:49600
	s_waitcnt lgkmcnt(9)
	v_mfma_f32_16x16x32_bf16 v[40:43], v[212:215], v[48:51], v[40:43]
	ds_read_b128 v[204:207], v123 offset:40512
	s_waitcnt lgkmcnt(9)
	v_mfma_f32_16x16x32_bf16 v[40:43], v[216:219], v[52:55], v[40:43]
	ds_read_b128 v[208:211], v123 offset:40448
	s_waitcnt lgkmcnt(9)
	v_mfma_f32_16x16x32_bf16 v[40:43], v[220:223], v[56:59], v[40:43]
	ds_read_b128 v[212:215], v121 offset:53760
	s_waitcnt lgkmcnt(9)
	v_mfma_f32_16x16x32_bf16 v[40:43], v[224:227], v[60:63], v[40:43]
	ds_read_b128 v[216:219], v121 offset:53824
	s_nop 6
	v_cvt_pk_bf16_f32 v40, v40, v41
	v_cvt_pk_bf16_f32 v41, v42, v43
	global_store_dwordx2 v[84:85], v[40:41], off offset:-64
	s_waitcnt lgkmcnt(8)
	v_mfma_f32_16x16x32_bf16 v[40:43], v[232:235], v[196:199], 0
	ds_read_b128 v[220:223], v121 offset:53888
	v_mfma_f32_16x16x32_bf16 v[40:43], v[228:231], v[200:203], v[40:43]
	ds_read_b128 v[224:227], v123 offset:42752
	s_waitcnt lgkmcnt(9)
	v_mfma_f32_16x16x32_bf16 v[40:43], v[236:239], v[48:51], v[40:43]
	ds_read_b128 v[232:235], v123 offset:42816
	s_waitcnt lgkmcnt(9)
	v_mfma_f32_16x16x32_bf16 v[40:43], v[244:247], v[52:55], v[40:43]
	ds_read_b128 v[228:231], v121 offset:58112
	s_waitcnt lgkmcnt(9)
	v_mfma_f32_16x16x32_bf16 v[40:43], v[248:251], v[56:59], v[40:43]
	ds_read_b128 v[236:239], v121 offset:58176
	s_waitcnt lgkmcnt(9)
	v_mfma_f32_16x16x32_bf16 v[40:43], v[252:255], v[60:63], v[40:43]
	ds_read_b128 v[244:247], v121 offset:58240
	s_nop 6
	v_cvt_pk_bf16_f32 v40, v40, v41
	v_cvt_pk_bf16_f32 v41, v42, v43
	global_store_dwordx2 v[84:85], v[40:41], off offset:-32
	s_waitcnt lgkmcnt(8)
	v_mfma_f32_16x16x32_bf16 v[40:43], v[208:211], v[196:199], 0
	ds_read_b128 v[248:251], v121 offset:58304
	v_mfma_f32_16x16x32_bf16 v[40:43], v[204:207], v[200:203], v[40:43]
	ds_read_b128 v[252:255], v97
	s_waitcnt lgkmcnt(9)
	v_mfma_f32_16x16x32_bf16 v[40:43], v[212:215], v[48:51], v[40:43]
	ds_read_b128 v[208:211], v123 offset:17408
	s_waitcnt lgkmcnt(9)
	v_mfma_f32_16x16x32_bf16 v[40:43], v[216:219], v[52:55], v[40:43]
	ds_read_b128 v[204:207], v123 offset:17472
	s_waitcnt lgkmcnt(9)
	v_mfma_f32_16x16x32_bf16 v[40:43], v[220:223], v[56:59], v[40:43]
	ds_read_b128 v[212:215], v97 offset:64
	ds_read_b128 v[44:47], v121 offset:53952
	s_waitcnt lgkmcnt(0)
	v_mfma_f32_16x16x32_bf16 v[40:43], v[44:47], v[60:63], v[40:43]
	s_nop 7
	v_cvt_pk_bf16_f32 v40, v40, v41
	v_cvt_pk_bf16_f32 v41, v42, v43
	global_store_dwordx2 v[84:85], v[40:41], off
	v_mfma_f32_16x16x32_bf16 v[32:35], v[224:227], v[196:199], 0
	ds_read_b128 v[216:219], v123 offset:19712
	v_mfma_f32_16x16x32_bf16 v[32:35], v[232:235], v[200:203], v[32:35]
	ds_read_b128 v[220:223], v123 offset:19776
	v_mfma_f32_16x16x32_bf16 v[32:35], v[228:231], v[48:51], v[32:35]
	ds_read_b128 v[196:199], v97 offset:128
	v_mfma_f32_16x16x32_bf16 v[32:35], v[236:239], v[52:55], v[32:35]
	ds_read_b128 v[224:227], v123 offset:22016
	v_mfma_f32_16x16x32_bf16 v[32:35], v[244:247], v[56:59], v[32:35]
	ds_read_b128 v[200:203], v123 offset:22080
	v_mfma_f32_16x16x32_bf16 v[32:35], v[248:251], v[60:63], v[32:35]
	ds_read_b128 v[232:235], v97 offset:192
	s_nop 7
	v_cvt_pk_bf16_f32 v32, v32, v33
	v_cvt_pk_bf16_f32 v33, v34, v35
	global_store_dwordx2 v[84:85], v[32:33], off offset:32
	ds_read_b128 v[36:39], v86 offset:35840
	ds_read_b128 v[32:35], v86 offset:35904
	v_lshl_add_u64 v[84:85], v[84:85], 0, s[50:51]
	v_pk_mul_f32 v[4:5], v[4:5], v[252:253]
	ds_read_b128 v[228:231], v123 offset:24320
	v_pk_mul_f32 v[6:7], v[6:7], v[254:255]
	s_waitcnt lgkmcnt(2)
	s_nop 0
	v_mfma_f32_16x16x32_bf16 v[4:7], v[208:211], v[36:39], v[4:7]
	ds_read_b128 v[236:239], v123 offset:24384
	s_waitcnt lgkmcnt(2)
	v_mfma_f32_16x16x32_bf16 v[4:7], v[204:207], v[32:35], v[4:7]
	ds_read_b128 v[244:247], v97 offset:256
	v_pk_mul_f32 v[0:1], v[0:1], v[212:213]
	ds_read_b128 v[248:251], v123 offset:26624
	v_pk_mul_f32 v[2:3], v[2:3], v[214:215]
	s_nop 1
	v_mfma_f32_16x16x32_bf16 v[0:3], v[216:219], v[36:39], v[0:3]
	ds_read_b128 v[252:255], v123 offset:26688
	v_mfma_f32_16x16x32_bf16 v[0:3], v[220:223], v[32:35], v[0:3]
	ds_read_b128 v[208:211], v97 offset:320
	v_pk_mul_f32 v[8:9], v[8:9], v[196:197]
	ds_read_b128 v[204:207], v123 offset:28928
	v_pk_mul_f32 v[10:11], v[10:11], v[198:199]
	s_nop 1
	v_mfma_f32_16x16x32_bf16 v[8:11], v[224:227], v[36:39], v[8:11]
	ds_read_b128 v[212:215], v123 offset:28992
	v_mfma_f32_16x16x32_bf16 v[8:11], v[200:203], v[32:35], v[8:11]
	ds_read_b128 v[216:219], v97 offset:384
	v_pk_mul_f32 v[12:13], v[12:13], v[232:233]
	ds_read_b128 v[220:223], v123 offset:31232
	v_pk_mul_f32 v[14:15], v[14:15], v[234:235]
	s_waitcnt lgkmcnt(9)
	s_nop 0
	v_mfma_f32_16x16x32_bf16 v[12:15], v[228:231], v[36:39], v[12:15]
	ds_read_b128 v[196:199], v123 offset:31296
	s_waitcnt lgkmcnt(9)
	v_mfma_f32_16x16x32_bf16 v[12:15], v[236:239], v[32:35], v[12:15]
	ds_read_b128 v[224:227], v97 offset:448
	s_waitcnt lgkmcnt(9)
	v_pk_mul_f32 v[16:17], v[16:17], v[244:245]
	v_pk_mul_f32 v[18:19], v[18:19], v[246:247]
	s_waitcnt lgkmcnt(8)
	s_nop 0
	v_mfma_f32_16x16x32_bf16 v[16:19], v[248:251], v[36:39], v[16:19]
	s_waitcnt lgkmcnt(7)
	v_mfma_f32_16x16x32_bf16 v[16:19], v[252:255], v[32:35], v[16:19]
	s_waitcnt lgkmcnt(6)
	v_pk_mul_f32 v[20:21], v[20:21], v[208:209]
	v_pk_mul_f32 v[22:23], v[22:23], v[210:211]
	s_waitcnt lgkmcnt(5)
	s_nop 0
	v_mfma_f32_16x16x32_bf16 v[20:23], v[204:207], v[36:39], v[20:23]
	s_waitcnt lgkmcnt(4)
	v_mfma_f32_16x16x32_bf16 v[20:23], v[212:215], v[32:35], v[20:23]
	s_waitcnt lgkmcnt(3)
	v_pk_mul_f32 v[24:25], v[24:25], v[216:217]
	v_pk_mul_f32 v[26:27], v[26:27], v[218:219]
	s_waitcnt lgkmcnt(2)
	s_nop 0
	v_mfma_f32_16x16x32_bf16 v[24:27], v[220:223], v[36:39], v[24:27]
	s_waitcnt lgkmcnt(1)
	v_mfma_f32_16x16x32_bf16 v[24:27], v[196:199], v[32:35], v[24:27]
	s_waitcnt lgkmcnt(0)
	v_pk_mul_f32 v[28:29], v[28:29], v[224:225]
	v_pk_mul_f32 v[30:31], v[30:31], v[226:227]
	ds_read_b128 v[40:43], v123 offset:33536
	s_waitcnt lgkmcnt(0)
	v_mfma_f32_16x16x32_bf16 v[28:31], v[40:43], v[36:39], v[28:31]
	ds_read_b128 v[36:39], v123 offset:33600
	s_waitcnt lgkmcnt(0)
	s_barrier
	v_mfma_f32_16x16x32_bf16 v[28:31], v[36:39], v[32:35], v[28:31]
	s_cbranch_scc0 .LBB0_1052

.LBB0_1461:
	s_or_b64 exec, exec, s[58:59]
	v_sub_f32_e32 v32, v66, v33
	v_exp_f32_e32 v66, v32
	v_sub_f32_e32 v32, v75, v35
	v_exp_f32_e32 v160, v32
	v_mov_b32_e32 v32, v38
	v_mov_b32_e32 v33, v36
	v_pk_mul_f32 v[32:33], v[66:67], v[32:33] op_sel_hi:[0,1]
	v_mov_b32_e32 v36, v39
	v_cvt_pk_bf16_f32 v39, v32, v33
	v_mov_b32_e32 v32, v42
	v_mov_b32_e32 v33, v40
	v_pk_mul_f32 v[32:33], v[66:67], v[32:33] op_sel_hi:[0,1]
	v_mov_b32_e32 v40, v43
	v_cvt_pk_bf16_f32 v38, v32, v33
	v_mov_b32_e32 v32, v46
	v_mov_b32_e32 v33, v44
	v_mov_b32_e32 v44, v47
	v_pk_mul_f32 v[34:35], v[160:161], v[36:37] op_sel_hi:[0,1]
	v_pk_mul_f32 v[36:37], v[160:161], v[40:41] op_sel_hi:[0,1]
	v_pk_mul_f32 v[32:33], v[66:67], v[32:33] op_sel_hi:[0,1]
	v_pk_mul_f32 v[40:41], v[160:161], v[44:45] op_sel_hi:[0,1]
	v_cvt_pk_bf16_f32 v35, v34, v35
	v_cvt_pk_bf16_f32 v34, v36, v37
	v_cvt_pk_bf16_f32 v37, v32, v33
	v_cvt_pk_bf16_f32 v33, v40, v41
	v_mov_b32_e32 v40, v50
	v_mov_b32_e32 v41, v48
	v_pk_mul_f32 v[40:41], v[66:67], v[40:41] op_sel_hi:[0,1]
	v_cvt_pk_bf16_f32 v36, v40, v41
	v_mov_b32_e32 v40, v56
	v_mov_b32_e32 v41, v52
	v_pk_mul_f32 v[40:41], v[66:67], v[40:41] op_sel_hi:[0,1]
	v_mov_b32_e32 v48, v51
	v_cvt_pk_bf16_f32 v51, v40, v41
	v_mov_b32_e32 v40, v96
	v_mov_b32_e32 v41, v60
	v_pk_mul_f32 v[42:43], v[160:161], v[48:49] op_sel_hi:[0,1]
	v_mov_b32_e32 v52, v57
	v_pk_mul_f32 v[40:41], v[66:67], v[40:41] op_sel_hi:[0,1]
	v_mov_b32_e32 v60, v97
	v_cvt_pk_bf16_f32 v32, v42, v43
	v_pk_mul_f32 v[42:43], v[160:161], v[52:53] op_sel_hi:[0,1]
	v_pk_mul_f32 v[44:45], v[160:161], v[60:61] op_sel_hi:[0,1]
	v_cvt_pk_bf16_f32 v50, v40, v41
	v_mov_b32_e32 v40, v62
	v_mov_b32_e32 v41, v98
	v_mov_b32_e32 v98, v63
	v_cvt_pk_bf16_f32 v43, v42, v43
	v_cvt_pk_bf16_f32 v42, v44, v45
	v_pk_mul_f32 v[40:41], v[66:67], v[40:41] op_sel_hi:[0,1]
	v_pk_mul_f32 v[44:45], v[160:161], v[98:99] op_sel_hi:[0,1]
	v_cvt_pk_bf16_f32 v49, v40, v41
	v_cvt_pk_bf16_f32 v41, v44, v45
	v_mov_b32_e32 v44, v54
	v_mov_b32_e32 v45, v58
	v_mov_b32_e32 v58, v55
	v_pk_mul_f32 v[44:45], v[66:67], v[44:45] op_sel_hi:[0,1]
	v_pk_mul_f32 v[46:47], v[160:161], v[58:59] op_sel_hi:[0,1]
	v_cvt_pk_bf16_f32 v48, v44, v45
	v_cvt_pk_bf16_f32 v40, v46, v47
	s_waitcnt lgkmcnt(0)
	s_barrier
	s_waitcnt lgkmcnt(0)
	ds_read_b128 v[216:219], v108
	v_add_u32_e32 v52, v109, v111
	v_add_u32_e32 v92, -1, v92
	s_add_i32 s73, s73, 1
	s_waitcnt lgkmcnt(0)
	v_pk_mul_f32 v[44:45], v[16:17], v[216:217]
	v_pk_mul_f32 v[46:47], v[18:19], v[218:219]
	v_cvt_pk_bf16_f32 v44, v44, v45
	v_cvt_pk_bf16_f32 v45, v46, v47
	ds_write_b64 v52, v[44:45] offset:45056
	ds_read_b128 v[220:223], v108 offset:64
	s_waitcnt lgkmcnt(0)
	v_pk_mul_f32 v[44:45], v[0:1], v[220:221]
	v_pk_mul_f32 v[46:47], v[2:3], v[222:223]
	v_cvt_pk_bf16_f32 v44, v44, v45
	v_cvt_pk_bf16_f32 v45, v46, v47
	ds_write_b64 v116, v[44:45] offset:45056
	ds_read_b128 v[224:227], v108 offset:128
	s_waitcnt lgkmcnt(0)
	v_pk_mul_f32 v[44:45], v[8:9], v[224:225]
	v_pk_mul_f32 v[46:47], v[10:11], v[226:227]
	v_cvt_pk_bf16_f32 v44, v44, v45
	v_cvt_pk_bf16_f32 v45, v46, v47
	ds_write_b64 v117, v[44:45] offset:45056
	ds_read_b128 v[228:231], v108 offset:192
	s_waitcnt lgkmcnt(0)
	v_pk_mul_f32 v[44:45], v[4:5], v[228:229]
	v_pk_mul_f32 v[46:47], v[6:7], v[230:231]
	v_cvt_pk_bf16_f32 v44, v44, v45
	v_cvt_pk_bf16_f32 v45, v46, v47
	ds_write_b64 v118, v[44:45] offset:45056
	ds_read_b128 v[232:235], v108 offset:256
	s_waitcnt lgkmcnt(0)
	v_pk_mul_f32 v[44:45], v[20:21], v[232:233]
	v_pk_mul_f32 v[46:47], v[22:23], v[234:235]
	v_cvt_pk_bf16_f32 v44, v44, v45
	v_cvt_pk_bf16_f32 v45, v46, v47
	ds_write_b64 v52, v[44:45] offset:45184
	ds_read_b128 v[236:239], v108 offset:320
	s_waitcnt lgkmcnt(0)
	v_pk_mul_f32 v[44:45], v[12:13], v[236:237]
	v_pk_mul_f32 v[46:47], v[14:15], v[238:239]
	v_cvt_pk_bf16_f32 v44, v44, v45
	v_cvt_pk_bf16_f32 v45, v46, v47
	ds_write_b64 v52, v[44:45] offset:45216
	ds_read_b128 v[244:247], v108 offset:384
	s_waitcnt lgkmcnt(0)
	v_pk_mul_f32 v[44:45], v[24:25], v[244:245]
	v_pk_mul_f32 v[46:47], v[26:27], v[246:247]
	v_cvt_pk_bf16_f32 v44, v44, v45
	v_cvt_pk_bf16_f32 v45, v46, v47
	ds_write_b64 v52, v[44:45] offset:45248
	ds_read_b128 v[248:251], v108 offset:448
	s_waitcnt lgkmcnt(0)
	v_pk_mul_f32 v[44:45], v[28:29], v[248:249]
	v_pk_mul_f32 v[46:47], v[30:31], v[250:251]
	v_cvt_pk_bf16_f32 v44, v44, v45
	v_cvt_pk_bf16_f32 v45, v46, v47
	ds_write_b64 v52, v[44:45] offset:45280
	ds_read_b128 v[252:255], v119 offset:17408
	ds_read_b128 v[216:219], v119 offset:17472
	ds_read_b128 v[220:223], v119 offset:21824
	ds_read_b128 v[224:227], v119 offset:17536
	ds_read_b128 v[228:231], v119 offset:17600
	ds_read_b128 v[232:235], v119 offset:21760
	ds_read_b128 v[236:239], v119 offset:21888
	ds_read_b128 v[244:247], v119 offset:21952
	ds_read_b128 v[248:251], v119 offset:26176
	v_add_u32_e32 v44, v109, v107
	ds_read_b128 v[60:63], v44
	ds_read_b128 v[52:55], v44 offset:64
	ds_read_b128 v[56:59], v44 offset:128
	ds_read_b128 v[44:47], v44 offset:192
	s_waitcnt lgkmcnt(3)
	v_mfma_f32_16x16x32_bf16 v[96:99], v[252:255], v[60:63], 0
	ds_read_b128 v[252:255], v119 offset:26112
	s_waitcnt lgkmcnt(3)
	v_mfma_f32_16x16x32_bf16 v[96:99], v[216:219], v[52:55], v[96:99]
	ds_read_b128 v[216:219], v119 offset:26240
	s_waitcnt lgkmcnt(3)
	v_mfma_f32_16x16x32_bf16 v[96:99], v[224:227], v[56:59], v[96:99]
	ds_read_b128 v[224:227], v119 offset:26304
	s_waitcnt lgkmcnt(3)
	v_mfma_f32_16x16x32_bf16 v[96:99], v[228:231], v[44:47], v[96:99]
	ds_read_b128 v[228:231], v119 offset:30528
	s_nop 6
	v_cndmask_b32_e64 v66, v96, 0, s[8:9]
	v_mfma_f32_16x16x32_bf16 v[160:163], v[232:235], v[60:63], 0
	ds_read_b128 v[232:235], v119 offset:30464
	v_cndmask_b32_e64 v75, v97, 0, s[10:11]
	v_cndmask_b32_e64 v95, v98, 0, s[12:13]
	v_cndmask_b32_e64 v97, v99, 0, s[14:15]
	v_mfma_f32_16x16x32_bf16 v[160:163], v[220:223], v[52:55], v[160:163]
	ds_read_b128 v[220:223], v119 offset:30592
	v_cvt_pk_bf16_f32 v96, v66, v75
	v_cvt_pk_bf16_f32 v97, v95, v97
	v_mfma_f32_16x16x32_bf16 v[160:163], v[236:239], v[56:59], v[160:163]
	v_mfma_f32_16x16x32_bf16 v[160:163], v[244:247], v[44:47], v[160:163]
	s_nop 6
	s_nop 0
	v_cndmask_b32_e64 v66, v160, 0, s[16:17]
	v_cndmask_b32_e64 v75, v161, 0, s[18:19]
	v_cndmask_b32_e64 v95, v162, 0, s[20:21]
	v_cndmask_b32_e64 v99, v163, 0, s[22:23]
	s_waitcnt lgkmcnt(5)
	v_mfma_f32_16x16x32_bf16 v[160:163], v[252:255], v[60:63], 0
	v_cvt_pk_bf16_f32 v98, v66, v75
	v_cvt_pk_bf16_f32 v99, v95, v99
	v_mfma_f32_16x16x32_bf16 v[160:163], v[248:251], v[52:55], v[160:163]
	s_waitcnt lgkmcnt(4)
	v_mfma_f32_16x16x32_bf16 v[160:163], v[216:219], v[56:59], v[160:163]
	s_waitcnt lgkmcnt(3)
	v_mfma_f32_16x16x32_bf16 v[160:163], v[224:227], v[44:47], v[160:163]
	s_nop 6
	s_nop 0
	v_cndmask_b32_e64 v66, v160, 0, s[24:25]
	v_cndmask_b32_e64 v95, v162, 0, s[28:29]
	v_cndmask_b32_e64 v160, v163, 0, s[30:31]
	v_cndmask_b32_e64 v75, v161, 0, s[26:27]
	v_cvt_pk_bf16_f32 v169, v95, v160
	s_waitcnt lgkmcnt(1)
	v_mfma_f32_16x16x32_bf16 v[160:163], v[232:235], v[60:63], 0
	v_cvt_pk_bf16_f32 v168, v66, v75
	v_mfma_f32_16x16x32_bf16 v[160:163], v[228:231], v[52:55], v[160:163]
	s_waitcnt lgkmcnt(0)
	v_mfma_f32_16x16x32_bf16 v[160:163], v[220:223], v[56:59], v[160:163]
	ds_read_b128 v[164:167], v119 offset:30656
	s_waitcnt lgkmcnt(0)
	s_barrier
	v_mfma_f32_16x16x32_bf16 v[160:163], v[164:167], v[44:47], v[160:163]
	s_nop 7
	v_cndmask_b32_e64 v66, v160, 0, s[34:35]
	v_cndmask_b32_e64 v75, v161, 0, s[36:37]
	v_cvt_pk_bf16_f32 v160, v66, v75
	v_add_u32_e32 v66, v110, v111
	v_cndmask_b32_e64 v95, v162, 0, s[38:39]
	v_cndmask_b32_e64 v161, v163, 0, s[40:41]
	v_add_u32_e32 v66, 0xf000, v66
	v_cvt_pk_bf16_f32 v161, v95, v161
	ds_write2_b64 v66, v[96:97], v[98:99] offset0:128 offset1:132
	ds_write2_b64 v66, v[168:169], v[160:161] offset0:136 offset1:140
	ds_write_b128 v120, v[48:51] offset:17408
	ds_write_b128 v120, v[36:39] offset:17424
	ds_write_b128 v120, v[40:43] offset:17552
	ds_write_b128 v120, v[32:35] offset:17568
	v_add_u32_e32 v160, v110, v107
	s_waitcnt lgkmcnt(0)
	s_barrier
	s_waitcnt lgkmcnt(0)
	ds_read_b128 v[216:219], v160 offset:62464
	ds_read_b128 v[220:223], v160 offset:62528
	ds_read_b128 v[224:227], v121 offset:35840
	ds_read_b128 v[228:231], v121 offset:35904
	ds_read_b128 v[232:235], v119 offset:45056
	ds_read_b128 v[236:239], v119 offset:45120
	ds_read_b128 v[244:247], v119 offset:45184
	ds_read_b128 v[248:251], v119 offset:45248
	ds_read_b128 v[252:255], v121 offset:38144
	s_waitcnt lgkmcnt(6)
	v_mfma_f32_16x16x32_bf16 v[48:51], v[224:227], v[216:219], 0
	ds_read_b128 v[224:227], v121 offset:38208
	v_ashrrev_i32_e32 v40, 9, v71
	v_cmp_gt_i32_e32 vcc, 32, v40
	v_lshlrev_b32_e32 v40, 1, v40
	s_waitcnt lgkmcnt(6)
	v_mfma_f32_16x16x32_bf16 v[48:51], v[228:231], v[220:223], v[48:51]
	ds_read_b128 v[228:231], v119 offset:49408
	v_subrev_u32_e32 v42, 63, v40
	v_or_b32_e32 v40, 1, v40
	s_waitcnt lgkmcnt(6)
	v_mfma_f32_16x16x32_bf16 v[48:51], v[232:235], v[60:63], v[48:51]
	ds_read_b128 v[232:235], v119 offset:49472
	v_ashrrev_i32_e32 v41, 31, v40
	v_cndmask_b32_e32 v41, 0, v41, vcc
	s_waitcnt lgkmcnt(6)
	v_mfma_f32_16x16x32_bf16 v[48:51], v[236:239], v[52:55], v[48:51]
	ds_read_b128 v[236:239], v119 offset:49536
	v_cndmask_b32_e32 v40, v42, v40, vcc
	v_cndmask_b32_e32 v66, v122, v123, vcc
	s_waitcnt lgkmcnt(6)
	v_mfma_f32_16x16x32_bf16 v[48:51], v[244:247], v[56:59], v[48:51]
	ds_read_b128 v[244:247], v119 offset:49600
	v_lshl_add_u64 v[42:43], s[94:95], 0, v[66:67]
	v_lshlrev_b64 v[40:41], 20, v[40:41]
	s_waitcnt lgkmcnt(6)
	v_mfma_f32_16x16x32_bf16 v[48:51], v[248:251], v[44:47], v[48:51]
	ds_read_b128 v[248:251], v121 offset:40512
	v_lshl_add_u64 v[40:41], v[42:43], 0, v[40:41]
	v_and_b32_e32 v42, 0x7fc00, v73
	v_lshlrev_b32_e32 v66, 1, v42
	s_nop 4
	v_cvt_pk_bf16_f32 v42, v48, v49
	v_cvt_pk_bf16_f32 v43, v50, v51
	s_waitcnt lgkmcnt(6)
	v_mfma_f32_16x16x32_bf16 v[48:51], v[252:255], v[216:219], 0
	ds_read_b128 v[252:255], v121 offset:40448
	v_lshl_add_u64 v[40:41], v[40:41], 0, v[66:67]
	v_mov_b32_e32 v95, v67
	v_lshl_add_u64 v[40:41], v[40:41], 0, v[94:95]
	s_waitcnt lgkmcnt(6)
	v_mfma_f32_16x16x32_bf16 v[48:51], v[224:227], v[220:223], v[48:51]
	ds_read_b128 v[224:227], v119 offset:53760
	v_lshl_add_u64 v[40:41], v[80:81], 1, v[40:41]
	v_mov_b32_e32 v75, v67
	s_waitcnt lgkmcnt(6)
	v_mfma_f32_16x16x32_bf16 v[48:51], v[228:231], v[60:63], v[48:51]
	ds_read_b128 v[228:231], v119 offset:53824
	v_lshl_add_u64 v[40:41], v[40:41], 0, v[74:75]
	global_store_dwordx2 v[40:41], v[42:43], off
	s_waitcnt lgkmcnt(6)
	v_mfma_f32_16x16x32_bf16 v[48:51], v[232:235], v[52:55], v[48:51]
	ds_read_b128 v[232:235], v119 offset:53888
	v_cmp_eq_u32_e32 vcc, -2, v92
	v_add_u32_e32 v73, 0xffff0000, v73
	s_waitcnt lgkmcnt(6)
	v_mfma_f32_16x16x32_bf16 v[48:51], v[236:239], v[56:59], v[48:51]
	ds_read_b128 v[236:239], v121 offset:42752
	v_subrev_u32_e32 v71, 64, v71
	s_or_b64 s[56:57], vcc, s[56:57]
	s_waitcnt lgkmcnt(6)
	v_mfma_f32_16x16x32_bf16 v[48:51], v[244:247], v[44:47], v[48:51]
	ds_read_b128 v[244:247], v119 offset:58112
	s_nop 6
	v_cvt_pk_bf16_f32 v42, v48, v49
	v_cvt_pk_bf16_f32 v43, v50, v51
	s_waitcnt lgkmcnt(5)
	v_mfma_f32_16x16x32_bf16 v[48:51], v[252:255], v[216:219], 0
	ds_read_b128 v[252:255], v119 offset:58176
	global_store_dwordx2 v[40:41], v[42:43], off offset:32
	v_mfma_f32_16x16x32_bf16 v[48:51], v[248:251], v[220:223], v[48:51]
	ds_read_b128 v[248:251], v119 offset:58240
	s_waitcnt lgkmcnt(6)
	v_mfma_f32_16x16x32_bf16 v[48:51], v[224:227], v[60:63], v[48:51]
	ds_read_b128 v[224:227], v119 offset:58304
	s_waitcnt lgkmcnt(6)
	v_mfma_f32_16x16x32_bf16 v[48:51], v[228:231], v[52:55], v[48:51]
	ds_read_b128 v[228:231], v112
	s_waitcnt lgkmcnt(6)
	v_mfma_f32_16x16x32_bf16 v[48:51], v[232:235], v[56:59], v[48:51]
	ds_read_b128 v[232:235], v121 offset:17408
	ds_read_b128 v[96:99], v119 offset:53952
	s_waitcnt lgkmcnt(0)
	v_mfma_f32_16x16x32_bf16 v[48:51], v[96:99], v[44:47], v[48:51]
	s_nop 7
	v_cvt_pk_bf16_f32 v42, v48, v49
	v_cvt_pk_bf16_f32 v43, v50, v51
	v_mfma_f32_16x16x32_bf16 v[36:39], v[236:239], v[216:219], 0
	ds_read_b128 v[216:219], v121 offset:17472
	ds_read_b128 v[236:239], v112 offset:64
	ds_read_b128 v[48:51], v121 offset:42816
	global_store_dwordx2 v[40:41], v[42:43], off offset:64
	s_waitcnt lgkmcnt(0)
	v_mfma_f32_16x16x32_bf16 v[32:35], v[48:51], v[220:223], v[36:39]
	ds_read_b128 v[220:223], v121 offset:19712
	s_nop 3
	v_mfma_f32_16x16x32_bf16 v[32:35], v[244:247], v[60:63], v[32:35]
	ds_read_b128 v[244:247], v121 offset:19776
	v_mfma_f32_16x16x32_bf16 v[32:35], v[252:255], v[52:55], v[32:35]
	ds_read_b128 v[252:255], v112 offset:128
	v_mfma_f32_16x16x32_bf16 v[32:35], v[248:251], v[56:59], v[32:35]
	ds_read_b128 v[248:251], v121 offset:22016
	v_mfma_f32_16x16x32_bf16 v[32:35], v[224:227], v[44:47], v[32:35]
	ds_read_b128 v[224:227], v121 offset:22080
	s_nop 7
	v_cvt_pk_bf16_f32 v32, v32, v33
	v_cvt_pk_bf16_f32 v33, v34, v35
	global_store_dwordx2 v[40:41], v[32:33], off offset:96
	ds_read_b128 v[36:39], v160 offset:35840
	ds_read_b128 v[32:35], v160 offset:35904
	v_pk_mul_f32 v[16:17], v[16:17], v[228:229]
	v_pk_mul_f32 v[18:19], v[18:19], v[230:231]
	ds_read_b128 v[228:231], v112 offset:192
	s_waitcnt lgkmcnt(2)
	v_mfma_f32_16x16x32_bf16 v[16:19], v[232:235], v[36:39], v[16:19]
	ds_read_b128 v[232:235], v121 offset:24320
	s_waitcnt lgkmcnt(2)
	v_mfma_f32_16x16x32_bf16 v[16:19], v[216:219], v[32:35], v[16:19]
	ds_read_b128 v[216:219], v121 offset:24384
	v_pk_mul_f32 v[0:1], v[0:1], v[236:237]
	v_pk_mul_f32 v[2:3], v[2:3], v[238:239]
	ds_read_b128 v[236:239], v112 offset:256
	s_nop 0
	v_mfma_f32_16x16x32_bf16 v[0:3], v[220:223], v[36:39], v[0:3]
	ds_read_b128 v[220:223], v121 offset:26624
	v_mfma_f32_16x16x32_bf16 v[0:3], v[244:247], v[32:35], v[0:3]
	ds_read_b128 v[244:247], v121 offset:26688
	v_pk_mul_f32 v[8:9], v[8:9], v[252:253]
	v_pk_mul_f32 v[10:11], v[10:11], v[254:255]
	ds_read_b128 v[252:255], v112 offset:320
	s_nop 0
	v_mfma_f32_16x16x32_bf16 v[8:11], v[248:251], v[36:39], v[8:11]
	ds_read_b128 v[248:251], v121 offset:28928
	v_mfma_f32_16x16x32_bf16 v[8:11], v[224:227], v[32:35], v[8:11]
	ds_read_b128 v[224:227], v121 offset:28992
	s_waitcnt lgkmcnt(8)
	v_pk_mul_f32 v[4:5], v[4:5], v[228:229]
	v_pk_mul_f32 v[6:7], v[6:7], v[230:231]
	ds_read_b128 v[228:231], v112 offset:384
	s_waitcnt lgkmcnt(8)
	v_mfma_f32_16x16x32_bf16 v[4:7], v[232:235], v[36:39], v[4:7]
	ds_read_b128 v[232:235], v121 offset:31232
	s_waitcnt lgkmcnt(8)
	v_mfma_f32_16x16x32_bf16 v[4:7], v[216:219], v[32:35], v[4:7]
	ds_read_b128 v[216:219], v121 offset:31296
	s_waitcnt lgkmcnt(8)
	v_pk_mul_f32 v[20:21], v[20:21], v[236:237]
	v_pk_mul_f32 v[22:23], v[22:23], v[238:239]
	ds_read_b128 v[236:239], v112 offset:448
	s_waitcnt lgkmcnt(8)
	v_mfma_f32_16x16x32_bf16 v[20:23], v[220:223], v[36:39], v[20:23]
	s_waitcnt lgkmcnt(7)
	v_mfma_f32_16x16x32_bf16 v[20:23], v[244:247], v[32:35], v[20:23]
	s_waitcnt lgkmcnt(6)
	v_pk_mul_f32 v[12:13], v[12:13], v[252:253]
	v_pk_mul_f32 v[14:15], v[14:15], v[254:255]
	s_waitcnt lgkmcnt(5)
	s_nop 0
	v_mfma_f32_16x16x32_bf16 v[12:15], v[248:251], v[36:39], v[12:15]
	s_waitcnt lgkmcnt(4)
	v_mfma_f32_16x16x32_bf16 v[12:15], v[224:227], v[32:35], v[12:15]
	s_waitcnt lgkmcnt(3)
	v_pk_mul_f32 v[24:25], v[24:25], v[228:229]
	v_pk_mul_f32 v[26:27], v[26:27], v[230:231]
	s_waitcnt lgkmcnt(2)
	s_nop 0
	v_mfma_f32_16x16x32_bf16 v[24:27], v[232:235], v[36:39], v[24:27]
	s_waitcnt lgkmcnt(1)
	v_mfma_f32_16x16x32_bf16 v[24:27], v[216:219], v[32:35], v[24:27]
	s_waitcnt lgkmcnt(0)
	v_pk_mul_f32 v[28:29], v[28:29], v[236:237]
	v_pk_mul_f32 v[30:31], v[30:31], v[238:239]
	ds_read_b128 v[40:43], v121 offset:33536
	s_waitcnt lgkmcnt(0)
	v_mfma_f32_16x16x32_bf16 v[28:31], v[40:43], v[36:39], v[28:31]
	ds_read_b128 v[36:39], v121 offset:33600
	s_waitcnt lgkmcnt(0)
	s_barrier
	v_mfma_f32_16x16x32_bf16 v[28:31], v[36:39], v[32:35], v[28:31]
	s_andn2_b64 exec, exec, s[56:57]
	s_cbranch_execz .LBB0_1466

.LBB0_1476:
	s_or_b64 exec, exec, s[60:61]
	v_sub_f32_e32 v32, v73, v33
	v_exp_f32_e32 v156, v32
	v_sub_f32_e32 v32, v155, v35
	v_exp_f32_e32 v158, v32
	v_mov_b32_e32 v32, v36
	v_mov_b32_e32 v33, v38
	v_mov_b32_e32 v38, v37
	v_pk_mul_f32 v[32:33], v[156:157], v[32:33] op_sel_hi:[0,1]
	v_pk_mul_f32 v[34:35], v[158:159], v[38:39] op_sel_hi:[0,1]
	v_cvt_pk_bf16_f32 v36, v32, v33
	v_cvt_pk_bf16_f32 v32, v34, v35
	v_mov_b32_e32 v34, v40
	v_mov_b32_e32 v35, v42
	v_pk_mul_f32 v[34:35], v[156:157], v[34:35] op_sel_hi:[0,1]
	v_mov_b32_e32 v42, v41
	v_cvt_pk_bf16_f32 v37, v34, v35
	v_mov_b32_e32 v34, v44
	v_mov_b32_e32 v35, v46
	v_mov_b32_e32 v46, v45
	v_pk_mul_f32 v[38:39], v[158:159], v[42:43] op_sel_hi:[0,1]
	v_pk_mul_f32 v[34:35], v[156:157], v[34:35] op_sel_hi:[0,1]
	v_pk_mul_f32 v[40:41], v[158:159], v[46:47] op_sel_hi:[0,1]
	v_cvt_pk_bf16_f32 v33, v38, v39
	v_cvt_pk_bf16_f32 v38, v34, v35
	v_cvt_pk_bf16_f32 v34, v40, v41
	v_mov_b32_e32 v40, v48
	v_mov_b32_e32 v41, v50
	v_pk_mul_f32 v[40:41], v[156:157], v[40:41] op_sel_hi:[0,1]
	v_mov_b32_e32 v50, v49
	v_pk_mul_f32 v[42:43], v[158:159], v[50:51] op_sel_hi:[0,1]
	v_cvt_pk_bf16_f32 v39, v40, v41
	v_mov_b32_e32 v40, v52
	v_mov_b32_e32 v41, v54
	v_mov_b32_e32 v54, v53
	v_cvt_pk_bf16_f32 v35, v42, v43
	v_pk_mul_f32 v[40:41], v[156:157], v[40:41] op_sel_hi:[0,1]
	v_pk_mul_f32 v[42:43], v[158:159], v[54:55] op_sel_hi:[0,1]
	v_cvt_pk_bf16_f32 v44, v40, v41
	v_cvt_pk_bf16_f32 v40, v42, v43
	v_mov_b32_e32 v42, v56
	v_mov_b32_e32 v43, v60
	v_pk_mul_f32 v[42:43], v[156:157], v[42:43] op_sel_hi:[0,1]
	v_mov_b32_e32 v60, v57
	v_cvt_pk_bf16_f32 v45, v42, v43
	v_mov_b32_e32 v42, v92
	v_mov_b32_e32 v43, v94
	v_mov_b32_e32 v94, v93
	v_pk_mul_f32 v[46:47], v[158:159], v[60:61] op_sel_hi:[0,1]
	v_pk_mul_f32 v[42:43], v[156:157], v[42:43] op_sel_hi:[0,1]
	v_pk_mul_f32 v[48:49], v[158:159], v[94:95] op_sel_hi:[0,1]
	v_cvt_pk_bf16_f32 v41, v46, v47
	v_cvt_pk_bf16_f32 v46, v42, v43
	v_cvt_pk_bf16_f32 v42, v48, v49
	v_mov_b32_e32 v48, v62
	v_mov_b32_e32 v49, v58
	v_mov_b32_e32 v58, v63
	v_pk_mul_f32 v[48:49], v[156:157], v[48:49] op_sel_hi:[0,1]
	v_pk_mul_f32 v[50:51], v[158:159], v[58:59] op_sel_hi:[0,1]
	v_cvt_pk_bf16_f32 v47, v48, v49
	v_cvt_pk_bf16_f32 v43, v50, v51
	s_waitcnt lgkmcnt(0)
	s_barrier
	s_waitcnt lgkmcnt(0)
	ds_read_b128 v[216:219], v105
	v_add_u32_e32 v52, v107, v109
	v_add_u32_e32 v60, v107, v104
	v_cmp_eq_u32_e32 vcc, s75, v132
	v_lshl_add_u64 v[86:87], v[86:87], 0, s[56:57]
	s_waitcnt lgkmcnt(0)
	v_pk_mul_f32 v[48:49], v[12:13], v[216:217]
	v_pk_mul_f32 v[50:51], v[14:15], v[218:219]
	v_cvt_pk_bf16_f32 v48, v48, v49
	v_cvt_pk_bf16_f32 v49, v50, v51
	ds_write_b64 v52, v[48:49] offset:45056
	ds_read_b128 v[220:223], v105 offset:64
	v_lshl_add_u64 v[88:89], v[88:89], 0, s[56:57]
	v_lshl_add_u64 v[90:91], v[90:91], 0, s[56:57]
	s_or_b64 s[58:59], vcc, s[58:59]
	s_waitcnt lgkmcnt(0)
	v_pk_mul_f32 v[48:49], v[0:1], v[220:221]
	v_pk_mul_f32 v[50:51], v[2:3], v[222:223]
	v_cvt_pk_bf16_f32 v48, v48, v49
	v_cvt_pk_bf16_f32 v49, v50, v51
	ds_write_b64 v113, v[48:49] offset:45056
	ds_read_b128 v[224:227], v105 offset:128
	s_waitcnt lgkmcnt(0)
	v_pk_mul_f32 v[48:49], v[8:9], v[224:225]
	v_pk_mul_f32 v[50:51], v[10:11], v[226:227]
	v_cvt_pk_bf16_f32 v48, v48, v49
	v_cvt_pk_bf16_f32 v49, v50, v51
	ds_write_b64 v114, v[48:49] offset:45056
	ds_read_b128 v[228:231], v105 offset:192
	s_waitcnt lgkmcnt(0)
	v_pk_mul_f32 v[48:49], v[4:5], v[228:229]
	v_pk_mul_f32 v[50:51], v[6:7], v[230:231]
	v_cvt_pk_bf16_f32 v48, v48, v49
	v_cvt_pk_bf16_f32 v49, v50, v51
	ds_write_b64 v115, v[48:49] offset:45056
	ds_read_b128 v[232:235], v105 offset:256
	s_waitcnt lgkmcnt(0)
	v_pk_mul_f32 v[48:49], v[20:21], v[232:233]
	v_pk_mul_f32 v[50:51], v[22:23], v[234:235]
	v_cvt_pk_bf16_f32 v48, v48, v49
	v_cvt_pk_bf16_f32 v49, v50, v51
	ds_write_b64 v52, v[48:49] offset:45184
	ds_read_b128 v[236:239], v105 offset:320
	s_waitcnt lgkmcnt(0)
	v_pk_mul_f32 v[48:49], v[16:17], v[236:237]
	v_pk_mul_f32 v[50:51], v[18:19], v[238:239]
	v_cvt_pk_bf16_f32 v48, v48, v49
	v_cvt_pk_bf16_f32 v49, v50, v51
	ds_write_b64 v52, v[48:49] offset:45216
	ds_read_b128 v[244:247], v105 offset:384
	s_waitcnt lgkmcnt(0)
	v_pk_mul_f32 v[48:49], v[24:25], v[244:245]
	v_pk_mul_f32 v[50:51], v[26:27], v[246:247]
	v_cvt_pk_bf16_f32 v48, v48, v49
	v_cvt_pk_bf16_f32 v49, v50, v51
	ds_write_b64 v52, v[48:49] offset:45248
	ds_read_b128 v[248:251], v105 offset:448
	s_waitcnt lgkmcnt(0)
	v_pk_mul_f32 v[48:49], v[28:29], v[248:249]
	v_pk_mul_f32 v[50:51], v[30:31], v[250:251]
	v_cvt_pk_bf16_f32 v48, v48, v49
	v_cvt_pk_bf16_f32 v49, v50, v51
	ds_write_b64 v52, v[48:49] offset:45280
	ds_read_b128 v[252:255], v116 offset:17408
	ds_read_b128 v[216:219], v116 offset:17472
	ds_read_b128 v[220:223], v116 offset:21824
	ds_read_b128 v[224:227], v116 offset:17536
	ds_read_b128 v[228:231], v116 offset:17600
	ds_read_b128 v[232:235], v116 offset:21760
	ds_read_b128 v[236:239], v116 offset:21888
	ds_read_b128 v[244:247], v116 offset:21952
	ds_read_b128 v[248:251], v116 offset:26176
	ds_read_b128 v[48:51], v60
	ds_read_b128 v[52:55], v60 offset:64
	ds_read_b128 v[56:59], v60 offset:128
	ds_read_b128 v[60:63], v60 offset:192
	s_waitcnt lgkmcnt(3)
	v_mfma_f32_16x16x32_bf16 v[92:95], v[252:255], v[48:51], 0
	ds_read_b128 v[252:255], v116 offset:26112
	s_waitcnt lgkmcnt(3)
	v_mfma_f32_16x16x32_bf16 v[92:95], v[216:219], v[52:55], v[92:95]
	ds_read_b128 v[216:219], v116 offset:26240
	s_waitcnt lgkmcnt(3)
	v_mfma_f32_16x16x32_bf16 v[92:95], v[224:227], v[56:59], v[92:95]
	ds_read_b128 v[224:227], v116 offset:26304
	s_waitcnt lgkmcnt(3)
	v_mfma_f32_16x16x32_bf16 v[92:95], v[228:231], v[60:63], v[92:95]
	ds_read_b128 v[228:231], v116 offset:30528
	s_nop 6
	v_cndmask_b32_e64 v73, v92, 0, s[4:5]
	v_mfma_f32_16x16x32_bf16 v[156:159], v[232:235], v[48:51], 0
	ds_read_b128 v[232:235], v116 offset:30464
	v_cndmask_b32_e64 v92, 0, v93, s[6:7]
	v_cndmask_b32_e64 v93, v94, 0, s[8:9]
	v_cndmask_b32_e64 v94, v95, 0, s[10:11]
	v_mfma_f32_16x16x32_bf16 v[156:159], v[220:223], v[52:55], v[156:159]
	ds_read_b128 v[220:223], v116 offset:30592
	v_cvt_pk_bf16_f32 v92, v73, v92
	v_cvt_pk_bf16_f32 v93, v93, v94
	v_mfma_f32_16x16x32_bf16 v[156:159], v[236:239], v[56:59], v[156:159]
	v_mfma_f32_16x16x32_bf16 v[156:159], v[244:247], v[60:63], v[156:159]
	s_nop 6
	s_nop 0
	v_cndmask_b32_e64 v73, v156, 0, s[12:13]
	v_cndmask_b32_e64 v94, v157, 0, s[14:15]
	v_cndmask_b32_e64 v95, v158, 0, s[16:17]
	v_cndmask_b32_e64 v155, v159, 0, s[18:19]
	s_waitcnt lgkmcnt(5)
	v_mfma_f32_16x16x32_bf16 v[156:159], v[252:255], v[48:51], 0
	v_cvt_pk_bf16_f32 v94, v73, v94
	v_cvt_pk_bf16_f32 v95, v95, v155
	v_mfma_f32_16x16x32_bf16 v[156:159], v[248:251], v[52:55], v[156:159]
	s_waitcnt lgkmcnt(4)
	v_mfma_f32_16x16x32_bf16 v[156:159], v[216:219], v[56:59], v[156:159]
	s_waitcnt lgkmcnt(3)
	v_mfma_f32_16x16x32_bf16 v[156:159], v[224:227], v[60:63], v[156:159]
	s_nop 6
	s_nop 0
	v_cndmask_b32_e64 v73, v156, 0, s[20:21]
	v_cndmask_b32_e64 v155, v157, 0, s[22:23]
	v_cndmask_b32_e64 v156, v158, 0, s[24:25]
	v_cndmask_b32_e64 v157, v159, 0, s[26:27]
	v_cvt_pk_bf16_f32 v165, v156, v157
	s_waitcnt lgkmcnt(1)
	v_mfma_f32_16x16x32_bf16 v[156:159], v[232:235], v[48:51], 0
	v_cvt_pk_bf16_f32 v164, v73, v155
	v_mfma_f32_16x16x32_bf16 v[156:159], v[228:231], v[52:55], v[156:159]
	s_waitcnt lgkmcnt(0)
	v_mfma_f32_16x16x32_bf16 v[156:159], v[220:223], v[56:59], v[156:159]
	ds_read_b128 v[160:163], v116 offset:30656
	s_waitcnt lgkmcnt(0)
	s_barrier
	v_mfma_f32_16x16x32_bf16 v[156:159], v[160:163], v[60:63], v[156:159]
	s_nop 7
	v_cndmask_b32_e64 v73, v156, 0, s[28:29]
	v_cndmask_b32_e64 v155, v157, 0, s[30:31]
	v_cvt_pk_bf16_f32 v156, v73, v155
	v_add_u32_e32 v73, v108, v109
	v_cndmask_b32_e64 v157, v158, 0, s[34:35]
	v_cndmask_b32_e64 v158, v159, 0, s[36:37]
	v_add_u32_e32 v73, 0xf000, v73
	v_cvt_pk_bf16_f32 v157, v157, v158
	ds_write2_b64 v73, v[92:93], v[94:95] offset0:128 offset1:132
	ds_write2_b64 v73, v[164:165], v[156:157] offset0:136 offset1:140
	ds_write_b128 v117, v[36:39] offset:17408
	ds_write_b128 v117, v[44:47] offset:17424
	ds_write_b128 v117, v[32:35] offset:17552
	ds_write_b128 v117, v[40:43] offset:17568
	v_add_u32_e32 v46, v108, v104
	s_waitcnt lgkmcnt(0)
	s_barrier
	s_waitcnt lgkmcnt(0)
	ds_read_b128 v[216:219], v46 offset:62464
	ds_read_b128 v[220:223], v46 offset:62528
	ds_read_b128 v[224:227], v118 offset:35840
	ds_read_b128 v[228:231], v118 offset:35904
	ds_read_b128 v[232:235], v116 offset:45056
	ds_read_b128 v[236:239], v116 offset:45120
	ds_read_b128 v[244:247], v116 offset:45184
	ds_read_b128 v[248:251], v116 offset:45248
	ds_read_b128 v[252:255], v118 offset:38208
	s_waitcnt lgkmcnt(6)
	v_mfma_f32_16x16x32_bf16 v[42:45], v[224:227], v[216:219], 0
	ds_read_b128 v[224:227], v118 offset:38144
	v_lshlrev_b64 v[32:33], 11, v[64:65]
	v_lshl_add_u64 v[32:33], v[84:85], 0, v[32:33]
	v_add_u32_e32 v64, 64, v64
	s_waitcnt lgkmcnt(6)
	v_mfma_f32_16x16x32_bf16 v[42:45], v[228:231], v[220:223], v[42:45]
	ds_read_b128 v[228:231], v116 offset:49408
	s_waitcnt lgkmcnt(6)
	v_mfma_f32_16x16x32_bf16 v[42:45], v[232:235], v[48:51], v[42:45]
	ds_read_b128 v[232:235], v116 offset:49472
	s_waitcnt lgkmcnt(6)
	v_mfma_f32_16x16x32_bf16 v[42:45], v[236:239], v[52:55], v[42:45]
	ds_read_b128 v[236:239], v116 offset:49536
	s_waitcnt lgkmcnt(6)
	v_mfma_f32_16x16x32_bf16 v[42:45], v[244:247], v[56:59], v[42:45]
	ds_read_b128 v[244:247], v116 offset:49600
	s_waitcnt lgkmcnt(6)
	v_mfma_f32_16x16x32_bf16 v[42:45], v[248:251], v[60:63], v[42:45]
	ds_read_b128 v[248:251], v118 offset:40512
	s_nop 6
	v_cvt_pk_bf16_f32 v42, v42, v43
	v_cvt_pk_bf16_f32 v43, v44, v45
	global_store_dwordx2 v[32:33], v[42:43], off
	s_waitcnt lgkmcnt(5)
	v_mfma_f32_16x16x32_bf16 v[42:45], v[224:227], v[216:219], 0
	ds_read_b128 v[224:227], v118 offset:40448
	v_mfma_f32_16x16x32_bf16 v[42:45], v[252:255], v[220:223], v[42:45]
	ds_read_b128 v[252:255], v116 offset:53760
	s_waitcnt lgkmcnt(6)
	v_mfma_f32_16x16x32_bf16 v[42:45], v[228:231], v[48:51], v[42:45]
	ds_read_b128 v[228:231], v116 offset:53824
	s_waitcnt lgkmcnt(6)
	v_mfma_f32_16x16x32_bf16 v[42:45], v[232:235], v[52:55], v[42:45]
	ds_read_b128 v[232:235], v116 offset:53888
	s_waitcnt lgkmcnt(6)
	v_mfma_f32_16x16x32_bf16 v[42:45], v[236:239], v[56:59], v[42:45]
	ds_read_b128 v[236:239], v118 offset:42752
	s_waitcnt lgkmcnt(6)
	v_mfma_f32_16x16x32_bf16 v[42:45], v[244:247], v[60:63], v[42:45]
	ds_read_b128 v[244:247], v116 offset:58112
	s_nop 6
	v_cvt_pk_bf16_f32 v42, v42, v43
	v_cvt_pk_bf16_f32 v43, v44, v45
	global_store_dwordx2 v[32:33], v[42:43], off offset:32
	s_waitcnt lgkmcnt(5)
	v_mfma_f32_16x16x32_bf16 v[42:45], v[224:227], v[216:219], 0
	ds_read_b128 v[224:227], v116 offset:58176
	v_mfma_f32_16x16x32_bf16 v[42:45], v[248:251], v[220:223], v[42:45]
	ds_read_b128 v[248:251], v116 offset:58240
	s_waitcnt lgkmcnt(6)
	v_mfma_f32_16x16x32_bf16 v[42:45], v[252:255], v[48:51], v[42:45]
	ds_read_b128 v[252:255], v116 offset:58304
	s_waitcnt lgkmcnt(6)
	v_mfma_f32_16x16x32_bf16 v[42:45], v[228:231], v[52:55], v[42:45]
	ds_read_b128 v[228:231], v110
	s_waitcnt lgkmcnt(6)
	v_mfma_f32_16x16x32_bf16 v[42:45], v[232:235], v[56:59], v[42:45]
	ds_read_b128 v[232:235], v118 offset:17408
	ds_read_b128 v[92:95], v116 offset:53952
	s_waitcnt lgkmcnt(0)
	v_mfma_f32_16x16x32_bf16 v[42:45], v[92:95], v[60:63], v[42:45]
	s_nop 7
	v_cvt_pk_bf16_f32 v42, v42, v43
	v_cvt_pk_bf16_f32 v43, v44, v45
	global_store_dwordx2 v[32:33], v[42:43], off offset:64
	v_mfma_f32_16x16x32_bf16 v[34:37], v[236:239], v[216:219], 0
	ds_read_b128 v[216:219], v118 offset:17472
	ds_read_b128 v[236:239], v110 offset:64
	ds_read_b128 v[42:45], v118 offset:42816
	s_waitcnt lgkmcnt(0)
	v_mfma_f32_16x16x32_bf16 v[34:37], v[42:45], v[220:223], v[34:37]
	ds_read_b128 v[220:223], v118 offset:19712
	v_mfma_f32_16x16x32_bf16 v[34:37], v[244:247], v[48:51], v[34:37]
	ds_read_b128 v[244:247], v118 offset:19776
	v_mfma_f32_16x16x32_bf16 v[34:37], v[224:227], v[52:55], v[34:37]
	ds_read_b128 v[224:227], v110 offset:128
	v_mfma_f32_16x16x32_bf16 v[34:37], v[248:251], v[56:59], v[34:37]
	ds_read_b128 v[248:251], v118 offset:22016
	v_mfma_f32_16x16x32_bf16 v[34:37], v[252:255], v[60:63], v[34:37]
	ds_read_b128 v[252:255], v118 offset:22080
	s_nop 7
	v_cvt_pk_bf16_f32 v34, v34, v35
	v_cvt_pk_bf16_f32 v35, v36, v37
	global_store_dwordx2 v[32:33], v[34:35], off offset:96
	ds_read_b128 v[36:39], v46 offset:35840
	ds_read_b128 v[32:35], v46 offset:35904
	v_pk_mul_f32 v[12:13], v[12:13], v[228:229]
	v_pk_mul_f32 v[14:15], v[14:15], v[230:231]
	ds_read_b128 v[228:231], v110 offset:192
	s_waitcnt lgkmcnt(2)
	v_mfma_f32_16x16x32_bf16 v[12:15], v[232:235], v[36:39], v[12:15]
	ds_read_b128 v[232:235], v118 offset:24320
	s_waitcnt lgkmcnt(2)
	v_mfma_f32_16x16x32_bf16 v[12:15], v[216:219], v[32:35], v[12:15]
	ds_read_b128 v[216:219], v118 offset:24384
	v_pk_mul_f32 v[0:1], v[0:1], v[236:237]
	v_pk_mul_f32 v[2:3], v[2:3], v[238:239]
	ds_read_b128 v[236:239], v110 offset:256
	s_nop 0
	v_mfma_f32_16x16x32_bf16 v[0:3], v[220:223], v[36:39], v[0:3]
	ds_read_b128 v[220:223], v118 offset:26624
	v_mfma_f32_16x16x32_bf16 v[0:3], v[244:247], v[32:35], v[0:3]
	ds_read_b128 v[244:247], v118 offset:26688
	v_pk_mul_f32 v[8:9], v[8:9], v[224:225]
	v_pk_mul_f32 v[10:11], v[10:11], v[226:227]
	ds_read_b128 v[224:227], v110 offset:320
	s_nop 0
	v_mfma_f32_16x16x32_bf16 v[8:11], v[248:251], v[36:39], v[8:11]
	ds_read_b128 v[248:251], v118 offset:28928
	v_mfma_f32_16x16x32_bf16 v[8:11], v[252:255], v[32:35], v[8:11]
	ds_read_b128 v[252:255], v118 offset:28992
	s_waitcnt lgkmcnt(8)
	v_pk_mul_f32 v[4:5], v[4:5], v[228:229]
	v_pk_mul_f32 v[6:7], v[6:7], v[230:231]
	ds_read_b128 v[228:231], v110 offset:384
	s_waitcnt lgkmcnt(8)
	v_mfma_f32_16x16x32_bf16 v[4:7], v[232:235], v[36:39], v[4:7]
	ds_read_b128 v[232:235], v118 offset:31232
	s_waitcnt lgkmcnt(8)
	v_mfma_f32_16x16x32_bf16 v[4:7], v[216:219], v[32:35], v[4:7]
	ds_read_b128 v[216:219], v118 offset:31296
	s_waitcnt lgkmcnt(8)
	v_pk_mul_f32 v[20:21], v[20:21], v[236:237]
	v_pk_mul_f32 v[22:23], v[22:23], v[238:239]
	ds_read_b128 v[236:239], v110 offset:448
	s_waitcnt lgkmcnt(8)
	v_mfma_f32_16x16x32_bf16 v[20:23], v[220:223], v[36:39], v[20:23]
	s_waitcnt lgkmcnt(7)
	v_mfma_f32_16x16x32_bf16 v[20:23], v[244:247], v[32:35], v[20:23]
	s_waitcnt lgkmcnt(6)
	v_pk_mul_f32 v[16:17], v[16:17], v[224:225]
	v_pk_mul_f32 v[18:19], v[18:19], v[226:227]
	s_waitcnt lgkmcnt(5)
	s_nop 0
	v_mfma_f32_16x16x32_bf16 v[16:19], v[248:251], v[36:39], v[16:19]
	s_waitcnt lgkmcnt(4)
	v_mfma_f32_16x16x32_bf16 v[16:19], v[252:255], v[32:35], v[16:19]
	s_waitcnt lgkmcnt(3)
	v_pk_mul_f32 v[24:25], v[24:25], v[228:229]
	v_pk_mul_f32 v[26:27], v[26:27], v[230:231]
	s_waitcnt lgkmcnt(2)
	s_nop 0
	v_mfma_f32_16x16x32_bf16 v[24:27], v[232:235], v[36:39], v[24:27]
	s_waitcnt lgkmcnt(1)
	v_mfma_f32_16x16x32_bf16 v[24:27], v[216:219], v[32:35], v[24:27]
	s_waitcnt lgkmcnt(0)
	v_pk_mul_f32 v[28:29], v[28:29], v[236:237]
	v_pk_mul_f32 v[30:31], v[30:31], v[238:239]
	ds_read_b128 v[40:43], v118 offset:33536
	s_waitcnt lgkmcnt(0)
	v_mfma_f32_16x16x32_bf16 v[28:31], v[40:43], v[36:39], v[28:31]
	ds_read_b128 v[36:39], v118 offset:33600
	s_waitcnt lgkmcnt(0)
	s_barrier
	v_mfma_f32_16x16x32_bf16 v[28:31], v[36:39], v[32:35], v[28:31]
	s_andn2_b64 exec, exec, s[58:59]
	s_cbranch_execz .LBB0_1481

.LBB0_1493:
	s_or_b64 exec, exec, s[54:55]
	v_sub_f32_e32 v34, v56, v35
	v_exp_f32_e32 v98, v34
	v_sub_f32_e32 v34, v77, v39
	v_exp_f32_e32 v56, v34
	v_mov_b32_e32 v34, v44
	v_mov_b32_e32 v35, v40
	v_mov_b32_e32 v40, v45
	s_waitcnt lgkmcnt(0)
	s_barrier
	s_waitcnt lgkmcnt(0)
	ds_read_b128 v[216:219], v114
	v_add_u32_e32 v197, v115, v117
	v_pk_mul_f32 v[34:35], v[98:99], v[34:35] op_sel_hi:[0,1]
	v_pk_mul_f32 v[40:41], v[56:57], v[40:41] op_sel_hi:[0,1]
	v_cvt_pk_bf16_f32 v39, v34, v35
	s_waitcnt lgkmcnt(0)
	v_pk_mul_f32 v[44:45], v[0:1], v[216:217]
	v_pk_mul_f32 v[46:47], v[2:3], v[218:219]
	v_cvt_pk_bf16_f32 v44, v44, v45
	v_cvt_pk_bf16_f32 v45, v46, v47
	ds_write_b64 v197, v[44:45] offset:45056
	ds_read_b128 v[220:223], v114 offset:64
	v_cvt_pk_bf16_f32 v35, v40, v41
	v_mov_b32_e32 v41, v32
	v_mov_b32_e32 v32, v43
	v_pk_mul_f32 v[32:33], v[56:57], v[32:33] op_sel_hi:[0,1]
	v_cvt_pk_bf16_f32 v34, v32, v33
	s_waitcnt lgkmcnt(0)
	v_pk_mul_f32 v[32:33], v[4:5], v[220:221]
	v_pk_mul_f32 v[48:49], v[6:7], v[222:223]
	v_cvt_pk_bf16_f32 v32, v32, v33
	v_cvt_pk_bf16_f32 v33, v48, v49
	ds_write_b64 v143, v[32:33] offset:45056
	ds_read_b128 v[224:227], v114 offset:128
	v_mov_b32_e32 v40, v42
	v_pk_mul_f32 v[54:55], v[98:99], v[40:41] op_sel_hi:[0,1]
	v_cvt_pk_bf16_f32 v38, v54, v55
	v_mov_b32_e32 v32, v52
	s_waitcnt lgkmcnt(0)
	v_pk_mul_f32 v[54:55], v[12:13], v[224:225]
	v_pk_mul_f32 v[198:199], v[14:15], v[226:227]
	v_cvt_pk_bf16_f32 v54, v54, v55
	v_cvt_pk_bf16_f32 v55, v198, v199
	ds_write_b64 v144, v[54:55] offset:45056
	ds_read_b128 v[228:231], v114 offset:192
	v_mov_b32_e32 v33, v36
	v_pk_mul_f32 v[32:33], v[98:99], v[32:33] op_sel_hi:[0,1]
	v_mov_b32_e32 v36, v53
	v_pk_mul_f32 v[202:203], v[56:57], v[36:37] op_sel_hi:[0,1]
	v_cvt_pk_bf16_f32 v37, v32, v33
	s_waitcnt lgkmcnt(0)
	v_pk_mul_f32 v[32:33], v[8:9], v[228:229]
	v_pk_mul_f32 v[198:199], v[10:11], v[230:231]
	v_cvt_pk_bf16_f32 v32, v32, v33
	v_cvt_pk_bf16_f32 v33, v198, v199
	ds_write_b64 v145, v[32:33] offset:45056
	ds_read_b128 v[232:235], v114 offset:256
	v_cvt_pk_bf16_f32 v33, v202, v203
	v_mov_b32_e32 v203, v78
	v_mov_b32_e32 v78, v81
	v_pk_mul_f32 v[78:79], v[56:57], v[78:79] op_sel_hi:[0,1]
	s_waitcnt lgkmcnt(0)
	v_pk_mul_f32 v[198:199], v[20:21], v[232:233]
	v_pk_mul_f32 v[200:201], v[22:23], v[234:235]
	v_cvt_pk_bf16_f32 v198, v198, v199
	v_cvt_pk_bf16_f32 v199, v200, v201
	ds_write_b64 v197, v[198:199] offset:45184
	ds_read_b128 v[236:239], v114 offset:320
	v_mov_b32_e32 v202, v80
	v_cvt_pk_bf16_f32 v32, v78, v79
	v_add_u32_e32 v77, v115, v113
	v_pk_mul_f32 v[202:203], v[98:99], v[202:203] op_sel_hi:[0,1]
	s_waitcnt lgkmcnt(0)
	v_pk_mul_f32 v[78:79], v[16:17], v[236:237]
	v_pk_mul_f32 v[80:81], v[18:19], v[238:239]
	v_cvt_pk_bf16_f32 v78, v78, v79
	v_cvt_pk_bf16_f32 v79, v80, v81
	ds_write_b64 v197, v[78:79] offset:45216
	ds_read_b128 v[244:247], v114 offset:384
	ds_read_b128 v[40:43], v77
	ds_read_b128 v[44:47], v77 offset:64
	v_cvt_pk_bf16_f32 v36, v202, v203
	v_mov_b32_e32 v199, v82
	s_waitcnt lgkmcnt(2)
	v_pk_mul_f32 v[78:79], v[28:29], v[244:245]
	v_pk_mul_f32 v[80:81], v[30:31], v[246:247]
	v_cvt_pk_bf16_f32 v78, v78, v79
	v_cvt_pk_bf16_f32 v79, v80, v81
	ds_write_b64 v197, v[78:79] offset:45248
	ds_read_b128 v[248:251], v114 offset:448
	v_mov_b32_e32 v82, v85
	v_mov_b32_e32 v198, v84
	v_pk_mul_f32 v[84:85], v[56:57], v[82:83] op_sel_hi:[0,1]
	v_cvt_pk_bf16_f32 v201, v84, v85
	s_waitcnt lgkmcnt(0)
	v_pk_mul_f32 v[78:79], v[24:25], v[248:249]
	v_pk_mul_f32 v[80:81], v[26:27], v[250:251]
	v_cvt_pk_bf16_f32 v78, v78, v79
	v_cvt_pk_bf16_f32 v79, v80, v81
	ds_write_b64 v197, v[78:79] offset:45280
	ds_read_b128 v[252:255], v146 offset:17408
	ds_read_b128 v[216:219], v146 offset:17472
	ds_read_b128 v[220:223], v146 offset:17536
	ds_read_b128 v[224:227], v146 offset:17600
	ds_read_b128 v[228:231], v146 offset:21760
	ds_read_b128 v[232:235], v146 offset:21824
	ds_read_b128 v[236:239], v146 offset:21888
	ds_read_b128 v[244:247], v146 offset:26112
	ds_read_b128 v[248:251], v146 offset:26176
	v_mov_b32_e32 v84, v88
	v_mov_b32_e32 v85, v86
	v_mov_b32_e32 v86, v89
	v_pk_mul_f32 v[84:85], v[98:99], v[84:85] op_sel_hi:[0,1]
	v_pk_mul_f32 v[86:87], v[56:57], v[86:87] op_sel_hi:[0,1]
	v_cvt_pk_bf16_f32 v82, v84, v85
	v_cvt_pk_bf16_f32 v200, v86, v87
	s_waitcnt lgkmcnt(8)
	v_mfma_f32_16x16x32_bf16 v[78:81], v[252:255], v[40:43], 0
	ds_read_b128 v[252:255], v146 offset:26240
	ds_read_b128 v[48:51], v77 offset:128
	ds_read_b128 v[52:55], v77 offset:192
	v_mov_b32_e32 v88, v92
	s_waitcnt lgkmcnt(10)
	v_mfma_f32_16x16x32_bf16 v[78:81], v[216:219], v[44:47], v[78:81]
	ds_read_b128 v[216:219], v146 offset:26304
	v_mov_b32_e32 v89, v90
	v_pk_mul_f32 v[88:89], v[98:99], v[88:89] op_sel_hi:[0,1]
	v_mov_b32_e32 v90, v93
	s_waitcnt lgkmcnt(2)
	v_mfma_f32_16x16x32_bf16 v[84:87], v[220:223], v[48:51], v[78:81]
	ds_read_b128 v[220:223], v146 offset:30464
	v_mul_f32_e64 v198, v98, v198
	v_mul_f32_e64 v199, v98, v199
	v_cvt_pk_bf16_f32 v83, v198, v199
	ds_read_b128 v[210:213], v146 offset:21952
	v_pk_mul_f32 v[78:79], v[56:57], v[90:91] op_sel_hi:[0,1]
	v_cvt_pk_bf16_f32 v81, v88, v89
	s_waitcnt lgkmcnt(3)
	v_mfma_f32_16x16x32_bf16 v[84:87], v[224:227], v[52:55], v[84:87]
	ds_read_b128 v[224:227], v146 offset:30592
	v_cvt_pk_bf16_f32 v199, v78, v79
	v_mov_b32_e32 v79, v94
	v_mov_b32_e32 v94, v97
	v_mov_b32_e32 v78, v96
	v_mfma_f32_16x16x32_bf16 v[202:205], v[228:231], v[40:43], 0
	v_mul_f32_e64 v96, v56, v94
	v_mul_f32_e64 v97, v56, v95
	v_pk_mul_f32 v[78:79], v[98:99], v[78:79] op_sel_hi:[0,1]
	v_mfma_f32_16x16x32_bf16 v[88:91], v[232:235], v[44:47], v[202:205]
	v_cvt_pk_bf16_f32 v80, v78, v79
	v_cvt_pk_bf16_f32 v198, v96, v97
	v_cndmask_b32_e64 v56, v84, 0, s[4:5]
	v_mfma_f32_16x16x32_bf16 v[88:91], v[236:239], v[48:51], v[88:91]
	v_cndmask_b32_e64 v77, v85, 0, s[10:11]
	v_cndmask_b32_e64 v79, v86, 0, s[12:13]
	v_mfma_f32_16x16x32_bf16 v[92:95], v[244:247], v[40:43], 0
	v_cndmask_b32_e64 v96, v87, 0, s[14:15]
	v_cvt_pk_bf16_f32 v78, v56, v77
	v_mfma_f32_16x16x32_bf16 v[92:95], v[248:251], v[44:47], v[92:95]
	v_cvt_pk_bf16_f32 v79, v79, v96
	v_add_u32_e32 v74, -1, v74
	s_waitcnt lgkmcnt(1)
	v_mfma_f32_16x16x32_bf16 v[88:91], v[210:213], v[52:55], v[88:91]
	s_add_i32 s66, s66, 1
	v_mfma_f32_16x16x32_bf16 v[92:95], v[252:255], v[48:51], v[92:95]
	ds_read_b128 v[206:209], v146 offset:30528
	s_nop 4
	v_cndmask_b32_e64 v56, v88, 0, s[16:17]
	v_cndmask_b32_e64 v77, v89, 0, s[18:19]
	v_cndmask_b32_e64 v97, v90, 0, s[20:21]
	v_cndmask_b32_e64 v98, v91, 0, s[22:23]
	v_mfma_f32_16x16x32_bf16 v[84:87], v[216:219], v[52:55], v[92:95]
	v_cvt_pk_bf16_f32 v96, v56, v77
	v_cvt_pk_bf16_f32 v97, v97, v98
	v_mfma_f32_16x16x32_bf16 v[92:95], v[220:223], v[40:43], 0
	ds_read_b128 v[202:205], v146 offset:30656
	s_nop 2
	s_nop 0
	v_cndmask_b32_e64 v56, v84, 0, s[24:25]
	v_cndmask_b32_e64 v77, v85, 0, s[26:27]
	s_waitcnt lgkmcnt(1)
	v_mfma_f32_16x16x32_bf16 v[92:95], v[206:209], v[44:47], v[92:95]
	v_cndmask_b32_e64 v84, v86, 0, s[28:29]
	v_cndmask_b32_e64 v85, v87, 0, s[30:31]
	v_mfma_f32_16x16x32_bf16 v[88:91], v[224:227], v[48:51], v[92:95]
	s_barrier
	s_nop 2
	s_nop 0
	v_cvt_pk_bf16_f32 v93, v84, v85
	v_mfma_f32_16x16x32_bf16 v[84:87], v[202:205], v[52:55], v[88:91]
	v_cvt_pk_bf16_f32 v92, v56, v77
	s_nop 6
	v_cndmask_b32_e64 v56, v84, 0, s[34:35]
	v_cndmask_b32_e64 v77, v85, 0, s[36:37]
	v_cvt_pk_bf16_f32 v84, v56, v77
	v_add_u32_e32 v56, v116, v117
	v_cndmask_b32_e64 v85, v86, 0, s[38:39]
	v_cndmask_b32_e64 v86, v87, 0, s[40:41]
	v_add_u32_e32 v56, 0xf000, v56
	v_cvt_pk_bf16_f32 v85, v85, v86
	ds_write2_b64 v56, v[78:79], v[96:97] offset0:128 offset1:132
	ds_write2_b64 v56, v[92:93], v[84:85] offset0:136 offset1:140
	v_add_u32_e32 v56, v118, v119
	ds_write_b128 v56, v[80:83] offset:17408
	ds_write_b128 v56, v[36:39] offset:17424
	ds_write_b128 v56, v[198:201] offset:17552
	ds_write_b128 v56, v[32:35] offset:17568
	s_waitcnt lgkmcnt(0)
	s_barrier
	s_waitcnt lgkmcnt(0)
	ds_read_b128 v[216:219], v147 offset:35840
	ds_read_b128 v[220:223], v147 offset:35904
	ds_read_b128 v[224:227], v146 offset:45056
	ds_read_b128 v[228:231], v146 offset:49408
	ds_read_b128 v[232:235], v146 offset:53760
	ds_read_b128 v[236:239], v146 offset:45120
	ds_read_b128 v[244:247], v146 offset:45184
	ds_read_b128 v[248:251], v146 offset:45248
	ds_read_b128 v[252:255], v147 offset:38144
	v_add_u32_e32 v77, v116, v113
	ds_read_b128 v[78:81], v77 offset:62464
	ds_read_b128 v[82:85], v77 offset:62528
	s_waitcnt lgkmcnt(1)
	v_mfma_f32_16x16x32_bf16 v[32:35], v[216:219], v[78:81], 0
	ds_read_b128 v[216:219], v147 offset:38208
	s_waitcnt lgkmcnt(1)
	v_mfma_f32_16x16x32_bf16 v[32:35], v[220:223], v[82:85], v[32:35]
	ds_read_b128 v[220:223], v146 offset:49472
	v_ashrrev_i32_e32 v56, 9, v65
	v_cmp_gt_i32_e32 vcc, 32, v56
	v_mfma_f32_16x16x32_bf16 v[32:35], v[224:227], v[40:43], v[32:35]
	ds_read_b128 v[224:227], v146 offset:49536
	v_subrev_u32_e32 v65, 64, v65
	v_mfma_f32_16x16x32_bf16 v[32:35], v[236:239], v[44:47], v[32:35]
	ds_read_b128 v[236:239], v146 offset:49600
	v_mfma_f32_16x16x32_bf16 v[32:35], v[244:247], v[48:51], v[32:35]
	ds_read_b128 v[244:247], v147 offset:40448
	v_mfma_f32_16x16x32_bf16 v[32:35], v[248:251], v[52:55], v[32:35]
	ds_read_b128 v[248:251], v147 offset:40512
	v_mfma_f32_16x16x32_bf16 v[86:89], v[252:255], v[78:81], 0
	ds_read_b128 v[252:255], v146 offset:53824
	s_waitcnt lgkmcnt(6)
	v_mfma_f32_16x16x32_bf16 v[36:39], v[216:219], v[82:85], v[86:89]
	ds_read_b128 v[216:219], v146 offset:53888
	s_nop 6
	v_mfma_f32_16x16x32_bf16 v[36:39], v[228:231], v[40:43], v[36:39]
	ds_read_b128 v[228:231], v146 offset:53952
	s_waitcnt lgkmcnt(7)
	v_mfma_f32_16x16x32_bf16 v[36:39], v[220:223], v[44:47], v[36:39]
	ds_read_b128 v[220:223], v147 offset:42752
	s_waitcnt lgkmcnt(7)
	v_mfma_f32_16x16x32_bf16 v[36:39], v[224:227], v[48:51], v[36:39]
	ds_read_b128 v[224:227], v147 offset:42816
	s_waitcnt lgkmcnt(7)
	v_mfma_f32_16x16x32_bf16 v[36:39], v[236:239], v[52:55], v[36:39]
	ds_read_b128 v[236:239], v146 offset:58176
	s_waitcnt lgkmcnt(7)
	v_mfma_f32_16x16x32_bf16 v[90:93], v[244:247], v[78:81], 0
	ds_read_b128 v[244:247], v146 offset:58304
	s_waitcnt lgkmcnt(7)
	v_mfma_f32_16x16x32_bf16 v[86:89], v[248:251], v[82:85], v[90:93]
	ds_read_b128 v[248:251], v146 offset:58240
	s_nop 5
	v_mfma_f32_16x16x32_bf16 v[86:89], v[232:235], v[40:43], v[86:89]
	ds_read_b128 v[232:235], v147 offset:17408
	s_waitcnt lgkmcnt(8)
	v_mfma_f32_16x16x32_bf16 v[86:89], v[252:255], v[44:47], v[86:89]
	ds_read_b128 v[252:255], v120
	s_waitcnt lgkmcnt(8)
	v_mfma_f32_16x16x32_bf16 v[86:89], v[216:219], v[48:51], v[86:89]
	ds_read_b128 v[216:219], v147 offset:17472
	s_waitcnt lgkmcnt(8)
	v_mfma_f32_16x16x32_bf16 v[86:89], v[228:231], v[52:55], v[86:89]
	ds_read_b128 v[228:231], v120 offset:64
	ds_read_b128 v[198:201], v146 offset:58112
	s_waitcnt lgkmcnt(9)
	v_mfma_f32_16x16x32_bf16 v[78:81], v[220:223], v[78:81], 0
	ds_read_b128 v[220:223], v147 offset:19712
	v_lshlrev_b32_e32 v94, 1, v56
	v_subrev_u32_e32 v96, 63, v94
	v_cndmask_b32_e32 v56, v148, v149, vcc
	s_waitcnt lgkmcnt(9)
	v_mfma_f32_16x16x32_bf16 v[78:81], v[224:227], v[82:85], v[78:81]
	ds_read_b128 v[224:227], v147 offset:19776
	v_or_b32_e32 v90, 1, v94
	v_ashrrev_i32_e32 v91, 31, v90
	s_waitcnt lgkmcnt(2)
	v_mfma_f32_16x16x32_bf16 v[40:43], v[198:201], v[40:43], v[78:81]
	v_cndmask_b32_e32 v95, 0, v91, vcc
	v_cndmask_b32_e32 v94, v96, v90, vcc
	s_nop 0
	v_mfma_f32_16x16x32_bf16 v[40:43], v[236:239], v[44:47], v[40:43]
	ds_read_b128 v[236:239], v147 offset:22016
	v_lshl_add_u64 v[44:45], s[94:95], 0, v[56:57]
	v_lshlrev_b64 v[46:47], 20, v[94:95]
	v_lshl_add_u64 v[94:95], v[44:45], 0, v[46:47]
	v_mfma_f32_16x16x32_bf16 v[40:43], v[248:251], v[48:51], v[40:43]
	ds_read_b128 v[248:251], v120 offset:128
	v_and_b32_e32 v44, 0x7fc00, v164
	v_lshlrev_b32_e32 v56, 1, v44
	v_cvt_pk_bf16_f32 v96, v32, v33
	v_mfma_f32_16x16x32_bf16 v[40:43], v[244:247], v[52:55], v[40:43]
	ds_read_b128 v[244:247], v147 offset:22080
	ds_read_b128 v[52:55], v77 offset:35840
	ds_read_b128 v[78:81], v77 offset:35904
	v_pk_mul_f32 v[0:1], v[0:1], v[252:253]
	v_pk_mul_f32 v[2:3], v[2:3], v[254:255]
	ds_read_b128 v[252:255], v147 offset:24320
	v_cvt_pk_bf16_f32 v97, v34, v35
	s_waitcnt lgkmcnt(2)
	v_mfma_f32_16x16x32_bf16 v[0:3], v[232:235], v[52:55], v[0:3]
	ds_read_b128 v[232:235], v147 offset:24384
	v_pk_mul_f32 v[4:5], v[4:5], v[228:229]
	v_pk_mul_f32 v[6:7], v[6:7], v[230:231]
	ds_read_b128 v[228:231], v147 offset:26624
	s_waitcnt lgkmcnt(3)
	v_mfma_f32_16x16x32_bf16 v[0:3], v[216:219], v[78:81], v[0:3]
	ds_read_b128 v[216:219], v120 offset:256
	v_lshl_add_u64 v[94:95], v[94:95], 0, v[56:57]
	v_mov_b32_e32 v77, v57
	v_lshl_add_u64 v[94:95], v[94:95], 0, v[76:77]
	v_mfma_f32_16x16x32_bf16 v[4:7], v[220:223], v[52:55], v[4:7]
	ds_read_b128 v[220:223], v147 offset:26688
	v_lshl_add_u64 v[94:95], v[58:59], 1, v[94:95]
	v_lshlrev_b32_e32 v56, 1, v112
	v_mfma_f32_16x16x32_bf16 v[4:7], v[224:227], v[78:81], v[4:7]
	ds_read_b128 v[224:227], v120 offset:320
	ds_read_b128 v[90:93], v120 offset:192
	v_pk_mul_f32 v[12:13], v[12:13], v[248:249]
	v_pk_mul_f32 v[14:15], v[14:15], v[250:251]
	ds_read_b128 v[248:251], v147 offset:28992
	v_lshl_add_u64 v[94:95], v[94:95], 0, v[56:57]
	v_mfma_f32_16x16x32_bf16 v[12:15], v[236:239], v[52:55], v[12:15]
	ds_read_b128 v[236:239], v147 offset:31232
	s_waitcnt lgkmcnt(2)
	v_pk_mul_f32 v[8:9], v[8:9], v[90:91]
	v_pk_mul_f32 v[10:11], v[10:11], v[92:93]
	v_mfma_f32_16x16x32_bf16 v[12:15], v[244:247], v[78:81], v[12:15]
	ds_read_b128 v[244:247], v120 offset:384
	v_cvt_pk_bf16_f32 v90, v36, v37
	v_cvt_pk_bf16_f32 v91, v38, v39
	v_cmp_eq_u32_e32 vcc, -2, v74
	v_mfma_f32_16x16x32_bf16 v[8:11], v[252:255], v[52:55], v[8:11]
	v_add_u32_e32 v164, 0xffff0000, v164
	s_or_b64 s[52:53], vcc, s[52:53]
	v_mfma_f32_16x16x32_bf16 v[8:11], v[232:235], v[78:81], v[8:11]
	v_pk_mul_f32 v[20:21], v[20:21], v[216:217]
	v_pk_mul_f32 v[22:23], v[22:23], v[218:219]
	ds_read_b128 v[82:85], v147 offset:28928
	global_store_dwordx2 v[94:95], v[96:97], off
	v_mfma_f32_16x16x32_bf16 v[20:23], v[228:231], v[52:55], v[20:23]
	v_pk_mul_f32 v[16:17], v[16:17], v[224:225]
	v_pk_mul_f32 v[18:19], v[18:19], v[226:227]
	v_mfma_f32_16x16x32_bf16 v[20:23], v[220:223], v[78:81], v[20:23]
	global_store_dwordx2 v[94:95], v[90:91], off offset:32
	s_waitcnt lgkmcnt(1)
	v_pk_mul_f32 v[28:29], v[28:29], v[244:245]
	s_waitcnt lgkmcnt(0)
	v_mfma_f32_16x16x32_bf16 v[16:19], v[82:85], v[52:55], v[16:19]
	v_mul_f32_e64 v30, v30, v246
	v_mul_f32_e64 v31, v31, v247
	v_cvt_pk_bf16_f32 v82, v86, v87
	v_cvt_pk_bf16_f32 v83, v88, v89
	v_mfma_f32_16x16x32_bf16 v[16:19], v[248:251], v[78:81], v[16:19]
	ds_read_b128 v[44:47], v147 offset:31296
	ds_read_b128 v[48:51], v120 offset:448
	ds_read_b128 v[36:39], v147 offset:33536
	global_store_dwordx2 v[94:95], v[82:83], off offset:64
	v_mfma_f32_16x16x32_bf16 v[28:31], v[236:239], v[52:55], v[28:31]
	ds_read_b128 v[32:35], v147 offset:33600
	s_waitcnt lgkmcnt(2)
	v_pk_mul_f32 v[24:25], v[24:25], v[48:49]
	v_pk_mul_f32 v[26:27], v[26:27], v[50:51]
	v_mfma_f32_16x16x32_bf16 v[28:31], v[44:47], v[78:81], v[28:31]
	s_nop 0
	s_waitcnt lgkmcnt(1)
	v_mfma_f32_16x16x32_bf16 v[24:27], v[36:39], v[52:55], v[24:27]
	v_cvt_pk_bf16_f32 v36, v40, v41
	v_cvt_pk_bf16_f32 v37, v42, v43
	global_store_dwordx2 v[94:95], v[36:37], off offset:96
	s_waitcnt lgkmcnt(0)
	v_mfma_f32_16x16x32_bf16 v[24:27], v[32:35], v[78:81], v[24:27]
	s_barrier
	s_andn2_b64 exec, exec, s[52:53]
	s_cbranch_execz .LBB0_1498

.LBB0_1506:
	s_or_b64 exec, exec, s[58:59]
	v_sub_f32_e32 v32, v156, v33
	v_exp_f32_e32 v156, v32
	v_sub_f32_e32 v32, v157, v35
	v_exp_f32_e32 v158, v32
	v_mov_b32_e32 v32, v36
	v_mov_b32_e32 v33, v38
	v_mov_b32_e32 v38, v37
	v_pk_mul_f32 v[32:33], v[156:157], v[32:33] op_sel_hi:[0,1]
	v_pk_mul_f32 v[34:35], v[158:159], v[38:39] op_sel_hi:[0,1]
	v_cvt_pk_bf16_f32 v36, v32, v33
	v_cvt_pk_bf16_f32 v32, v34, v35
	v_mov_b32_e32 v34, v40
	v_mov_b32_e32 v35, v42
	v_pk_mul_f32 v[34:35], v[156:157], v[34:35] op_sel_hi:[0,1]
	v_mov_b32_e32 v42, v41
	v_cvt_pk_bf16_f32 v37, v34, v35
	v_mov_b32_e32 v34, v44
	v_mov_b32_e32 v35, v46
	v_mov_b32_e32 v46, v45
	v_pk_mul_f32 v[38:39], v[158:159], v[42:43] op_sel_hi:[0,1]
	v_pk_mul_f32 v[34:35], v[156:157], v[34:35] op_sel_hi:[0,1]
	v_pk_mul_f32 v[40:41], v[158:159], v[46:47] op_sel_hi:[0,1]
	v_cvt_pk_bf16_f32 v33, v38, v39
	v_cvt_pk_bf16_f32 v38, v34, v35
	v_cvt_pk_bf16_f32 v34, v40, v41
	v_mov_b32_e32 v40, v48
	v_mov_b32_e32 v41, v50
	v_pk_mul_f32 v[40:41], v[156:157], v[40:41] op_sel_hi:[0,1]
	v_mov_b32_e32 v50, v49
	v_pk_mul_f32 v[42:43], v[158:159], v[50:51] op_sel_hi:[0,1]
	v_cvt_pk_bf16_f32 v39, v40, v41
	v_mov_b32_e32 v40, v52
	v_mov_b32_e32 v41, v54
	v_mov_b32_e32 v54, v53
	v_cvt_pk_bf16_f32 v35, v42, v43
	v_pk_mul_f32 v[40:41], v[156:157], v[40:41] op_sel_hi:[0,1]
	v_pk_mul_f32 v[42:43], v[158:159], v[54:55] op_sel_hi:[0,1]
	v_cvt_pk_bf16_f32 v44, v40, v41
	v_cvt_pk_bf16_f32 v40, v42, v43
	v_mov_b32_e32 v42, v56
	v_mov_b32_e32 v43, v60
	v_pk_mul_f32 v[42:43], v[156:157], v[42:43] op_sel_hi:[0,1]
	v_mov_b32_e32 v60, v57
	v_cvt_pk_bf16_f32 v45, v42, v43
	v_mov_b32_e32 v42, v86
	v_mov_b32_e32 v43, v88
	v_mov_b32_e32 v88, v87
	v_pk_mul_f32 v[46:47], v[158:159], v[60:61] op_sel_hi:[0,1]
	v_pk_mul_f32 v[42:43], v[156:157], v[42:43] op_sel_hi:[0,1]
	v_pk_mul_f32 v[48:49], v[158:159], v[88:89] op_sel_hi:[0,1]
	v_cvt_pk_bf16_f32 v41, v46, v47
	v_cvt_pk_bf16_f32 v46, v42, v43
	v_cvt_pk_bf16_f32 v42, v48, v49
	v_mov_b32_e32 v48, v62
	v_mov_b32_e32 v49, v58
	v_mov_b32_e32 v58, v63
	v_pk_mul_f32 v[48:49], v[156:157], v[48:49] op_sel_hi:[0,1]
	v_pk_mul_f32 v[50:51], v[158:159], v[58:59] op_sel_hi:[0,1]
	v_cvt_pk_bf16_f32 v47, v48, v49
	v_cvt_pk_bf16_f32 v43, v50, v51
	s_waitcnt lgkmcnt(0)
	s_barrier
	s_waitcnt lgkmcnt(0)
	ds_read_b128 v[216:219], v114
	v_add_u32_e32 v52, v115, v117
	v_add_u32_e32 v60, v115, v113
	v_cmp_eq_u32_e32 vcc, s74, v133
	v_lshl_add_u64 v[80:81], v[80:81], 0, s[54:55]
	s_waitcnt lgkmcnt(0)
	v_pk_mul_f32 v[48:49], v[12:13], v[216:217]
	v_pk_mul_f32 v[50:51], v[14:15], v[218:219]
	v_cvt_pk_bf16_f32 v48, v48, v49
	v_cvt_pk_bf16_f32 v49, v50, v51
	ds_write_b64 v52, v[48:49] offset:45056
	ds_read_b128 v[220:223], v114 offset:64
	v_lshl_add_u64 v[82:83], v[82:83], 0, s[54:55]
	v_lshl_add_u64 v[84:85], v[84:85], 0, s[54:55]
	s_or_b64 s[56:57], vcc, s[56:57]
	s_waitcnt lgkmcnt(0)
	v_pk_mul_f32 v[48:49], v[0:1], v[220:221]
	v_pk_mul_f32 v[50:51], v[2:3], v[222:223]
	v_cvt_pk_bf16_f32 v48, v48, v49
	v_cvt_pk_bf16_f32 v49, v50, v51
	ds_write_b64 v91, v[48:49] offset:45056
	ds_read_b128 v[224:227], v114 offset:128
	s_waitcnt lgkmcnt(0)
	v_pk_mul_f32 v[48:49], v[8:9], v[224:225]
	v_pk_mul_f32 v[50:51], v[10:11], v[226:227]
	v_cvt_pk_bf16_f32 v48, v48, v49
	v_cvt_pk_bf16_f32 v49, v50, v51
	ds_write_b64 v92, v[48:49] offset:45056
	ds_read_b128 v[228:231], v114 offset:192
	s_waitcnt lgkmcnt(0)
	v_pk_mul_f32 v[48:49], v[4:5], v[228:229]
	v_pk_mul_f32 v[50:51], v[6:7], v[230:231]
	v_cvt_pk_bf16_f32 v48, v48, v49
	v_cvt_pk_bf16_f32 v49, v50, v51
	ds_write_b64 v93, v[48:49] offset:45056
	ds_read_b128 v[232:235], v114 offset:256
	s_waitcnt lgkmcnt(0)
	v_pk_mul_f32 v[48:49], v[20:21], v[232:233]
	v_pk_mul_f32 v[50:51], v[22:23], v[234:235]
	v_cvt_pk_bf16_f32 v48, v48, v49
	v_cvt_pk_bf16_f32 v49, v50, v51
	ds_write_b64 v52, v[48:49] offset:45184
	ds_read_b128 v[236:239], v114 offset:320
	s_waitcnt lgkmcnt(0)
	v_pk_mul_f32 v[48:49], v[16:17], v[236:237]
	v_pk_mul_f32 v[50:51], v[18:19], v[238:239]
	v_cvt_pk_bf16_f32 v48, v48, v49
	v_cvt_pk_bf16_f32 v49, v50, v51
	ds_write_b64 v52, v[48:49] offset:45216
	ds_read_b128 v[244:247], v114 offset:384
	s_waitcnt lgkmcnt(0)
	v_pk_mul_f32 v[48:49], v[24:25], v[244:245]
	v_pk_mul_f32 v[50:51], v[26:27], v[246:247]
	v_cvt_pk_bf16_f32 v48, v48, v49
	v_cvt_pk_bf16_f32 v49, v50, v51
	ds_write_b64 v52, v[48:49] offset:45248
	ds_read_b128 v[248:251], v114 offset:448
	s_waitcnt lgkmcnt(0)
	v_pk_mul_f32 v[48:49], v[28:29], v[248:249]
	v_pk_mul_f32 v[50:51], v[30:31], v[250:251]
	v_cvt_pk_bf16_f32 v48, v48, v49
	v_cvt_pk_bf16_f32 v49, v50, v51
	ds_write_b64 v52, v[48:49] offset:45280
	ds_read_b128 v[252:255], v94 offset:17408
	ds_read_b128 v[216:219], v94 offset:17472
	ds_read_b128 v[220:223], v94 offset:21824
	ds_read_b128 v[224:227], v94 offset:17536
	ds_read_b128 v[228:231], v94 offset:17600
	ds_read_b128 v[232:235], v94 offset:21760
	ds_read_b128 v[236:239], v94 offset:21888
	ds_read_b128 v[244:247], v94 offset:21952
	ds_read_b128 v[248:251], v94 offset:26176
	ds_read_b128 v[48:51], v60
	ds_read_b128 v[52:55], v60 offset:64
	ds_read_b128 v[56:59], v60 offset:128
	ds_read_b128 v[60:63], v60 offset:192
	s_waitcnt lgkmcnt(3)
	v_mfma_f32_16x16x32_bf16 v[86:89], v[252:255], v[48:51], 0
	ds_read_b128 v[252:255], v94 offset:26112
	s_waitcnt lgkmcnt(3)
	v_mfma_f32_16x16x32_bf16 v[86:89], v[216:219], v[52:55], v[86:89]
	ds_read_b128 v[216:219], v94 offset:26240
	s_waitcnt lgkmcnt(3)
	v_mfma_f32_16x16x32_bf16 v[86:89], v[224:227], v[56:59], v[86:89]
	ds_read_b128 v[224:227], v94 offset:26304
	s_waitcnt lgkmcnt(3)
	v_mfma_f32_16x16x32_bf16 v[86:89], v[228:231], v[60:63], v[86:89]
	ds_read_b128 v[228:231], v94 offset:30528
	s_nop 6
	v_cndmask_b32_e64 v86, v86, 0, s[6:7]
	v_mfma_f32_16x16x32_bf16 v[156:159], v[232:235], v[48:51], 0
	ds_read_b128 v[232:235], v94 offset:30464
	v_cndmask_b32_e64 v87, 0, v87, s[8:9]
	v_cndmask_b32_e64 v88, v88, 0, s[10:11]
	v_cndmask_b32_e64 v89, v89, 0, s[12:13]
	v_mfma_f32_16x16x32_bf16 v[156:159], v[220:223], v[52:55], v[156:159]
	ds_read_b128 v[220:223], v94 offset:30592
	v_cvt_pk_bf16_f32 v86, v86, v87
	v_cvt_pk_bf16_f32 v87, v88, v89
	v_mfma_f32_16x16x32_bf16 v[156:159], v[236:239], v[56:59], v[156:159]
	v_mfma_f32_16x16x32_bf16 v[156:159], v[244:247], v[60:63], v[156:159]
	s_nop 6
	s_nop 0
	v_cndmask_b32_e64 v88, v156, 0, s[14:15]
	v_cndmask_b32_e64 v89, v157, 0, s[16:17]
	v_cndmask_b32_e64 v156, v158, 0, s[18:19]
	v_cndmask_b32_e64 v157, v159, 0, s[20:21]
	v_cvt_pk_bf16_f32 v88, v88, v89
	v_cvt_pk_bf16_f32 v89, v156, v157
	s_waitcnt lgkmcnt(5)
	v_mfma_f32_16x16x32_bf16 v[156:159], v[252:255], v[48:51], 0
	v_mfma_f32_16x16x32_bf16 v[156:159], v[248:251], v[52:55], v[156:159]
	s_waitcnt lgkmcnt(4)
	v_mfma_f32_16x16x32_bf16 v[156:159], v[216:219], v[56:59], v[156:159]
	s_waitcnt lgkmcnt(3)
	v_mfma_f32_16x16x32_bf16 v[156:159], v[224:227], v[60:63], v[156:159]
	s_nop 6
	s_nop 0
	v_cndmask_b32_e64 v156, v156, 0, s[22:23]
	v_cndmask_b32_e64 v157, v157, 0, s[24:25]
	v_cndmask_b32_e64 v158, v158, 0, s[26:27]
	v_cndmask_b32_e64 v159, v159, 0, s[28:29]
	v_cvt_pk_bf16_f32 v164, v156, v157
	v_cvt_pk_bf16_f32 v165, v158, v159
	s_waitcnt lgkmcnt(1)
	v_mfma_f32_16x16x32_bf16 v[156:159], v[232:235], v[48:51], 0
	v_mfma_f32_16x16x32_bf16 v[156:159], v[228:231], v[52:55], v[156:159]
	s_waitcnt lgkmcnt(0)
	v_mfma_f32_16x16x32_bf16 v[156:159], v[220:223], v[56:59], v[156:159]
	ds_read_b128 v[160:163], v94 offset:30656
	s_waitcnt lgkmcnt(0)
	s_barrier
	v_mfma_f32_16x16x32_bf16 v[156:159], v[160:163], v[60:63], v[156:159]
	s_nop 7
	v_cndmask_b32_e64 v156, v156, 0, s[30:31]
	v_cndmask_b32_e64 v157, v157, 0, s[34:35]
	v_cndmask_b32_e64 v158, v158, 0, s[36:37]
	v_cndmask_b32_e64 v159, v159, 0, s[38:39]
	v_cvt_pk_bf16_f32 v156, v156, v157
	v_cvt_pk_bf16_f32 v157, v158, v159
	v_add_u32_e32 v158, v116, v117
	v_add_u32_e32 v158, 0xf000, v158
	ds_write2_b64 v158, v[86:87], v[88:89] offset0:128 offset1:132
	ds_write2_b64 v158, v[164:165], v[156:157] offset0:136 offset1:140
	v_add_u32_e32 v86, v118, v119
	ds_write_b128 v86, v[36:39] offset:17408
	ds_write_b128 v86, v[44:47] offset:17424
	ds_write_b128 v86, v[32:35] offset:17552
	ds_write_b128 v86, v[40:43] offset:17568
	v_add_u32_e32 v46, v116, v113
	s_waitcnt lgkmcnt(0)
	s_barrier
	s_waitcnt lgkmcnt(0)
	ds_read_b128 v[216:219], v46 offset:62464
	ds_read_b128 v[220:223], v46 offset:62528
	ds_read_b128 v[224:227], v95 offset:35840
	ds_read_b128 v[228:231], v95 offset:35904
	ds_read_b128 v[232:235], v94 offset:45056
	ds_read_b128 v[236:239], v94 offset:45120
	ds_read_b128 v[244:247], v94 offset:45184
	ds_read_b128 v[248:251], v94 offset:45248
	ds_read_b128 v[252:255], v95 offset:38208
	s_waitcnt lgkmcnt(6)
	v_mfma_f32_16x16x32_bf16 v[42:45], v[224:227], v[216:219], 0
	ds_read_b128 v[224:227], v95 offset:38144
	v_lshlrev_b64 v[32:33], 11, v[70:71]
	v_lshl_add_u64 v[32:33], v[78:79], 0, v[32:33]
	v_add_u32_e32 v70, 64, v70
	s_waitcnt lgkmcnt(6)
	v_mfma_f32_16x16x32_bf16 v[42:45], v[228:231], v[220:223], v[42:45]
	ds_read_b128 v[228:231], v94 offset:49408
	s_waitcnt lgkmcnt(6)
	v_mfma_f32_16x16x32_bf16 v[42:45], v[232:235], v[48:51], v[42:45]
	ds_read_b128 v[232:235], v94 offset:49472
	s_waitcnt lgkmcnt(6)
	v_mfma_f32_16x16x32_bf16 v[42:45], v[236:239], v[52:55], v[42:45]
	ds_read_b128 v[236:239], v94 offset:49536
	s_waitcnt lgkmcnt(6)
	v_mfma_f32_16x16x32_bf16 v[42:45], v[244:247], v[56:59], v[42:45]
	ds_read_b128 v[244:247], v94 offset:49600
	s_waitcnt lgkmcnt(6)
	v_mfma_f32_16x16x32_bf16 v[42:45], v[248:251], v[60:63], v[42:45]
	ds_read_b128 v[248:251], v95 offset:40512
	s_nop 6
	v_cvt_pk_bf16_f32 v42, v42, v43
	v_cvt_pk_bf16_f32 v43, v44, v45
	global_store_dwordx2 v[32:33], v[42:43], off
	s_waitcnt lgkmcnt(5)
	v_mfma_f32_16x16x32_bf16 v[42:45], v[224:227], v[216:219], 0
	ds_read_b128 v[224:227], v95 offset:40448
	v_mfma_f32_16x16x32_bf16 v[42:45], v[252:255], v[220:223], v[42:45]
	ds_read_b128 v[252:255], v94 offset:53760
	s_waitcnt lgkmcnt(6)
	v_mfma_f32_16x16x32_bf16 v[42:45], v[228:231], v[48:51], v[42:45]
	ds_read_b128 v[228:231], v94 offset:53824
	s_waitcnt lgkmcnt(6)
	v_mfma_f32_16x16x32_bf16 v[42:45], v[232:235], v[52:55], v[42:45]
	ds_read_b128 v[232:235], v94 offset:53888
	s_waitcnt lgkmcnt(6)
	v_mfma_f32_16x16x32_bf16 v[42:45], v[236:239], v[56:59], v[42:45]
	ds_read_b128 v[236:239], v95 offset:42752
	s_waitcnt lgkmcnt(6)
	v_mfma_f32_16x16x32_bf16 v[42:45], v[244:247], v[60:63], v[42:45]
	ds_read_b128 v[244:247], v94 offset:58112
	s_nop 6
	v_cvt_pk_bf16_f32 v42, v42, v43
	v_cvt_pk_bf16_f32 v43, v44, v45
	global_store_dwordx2 v[32:33], v[42:43], off offset:32
	s_waitcnt lgkmcnt(5)
	v_mfma_f32_16x16x32_bf16 v[42:45], v[224:227], v[216:219], 0
	ds_read_b128 v[224:227], v94 offset:58176
	v_mfma_f32_16x16x32_bf16 v[42:45], v[248:251], v[220:223], v[42:45]
	ds_read_b128 v[248:251], v94 offset:58240
	s_waitcnt lgkmcnt(6)
	v_mfma_f32_16x16x32_bf16 v[42:45], v[252:255], v[48:51], v[42:45]
	ds_read_b128 v[252:255], v94 offset:58304
	s_waitcnt lgkmcnt(6)
	v_mfma_f32_16x16x32_bf16 v[42:45], v[228:231], v[52:55], v[42:45]
	ds_read_b128 v[228:231], v120
	s_waitcnt lgkmcnt(6)
	v_mfma_f32_16x16x32_bf16 v[42:45], v[232:235], v[56:59], v[42:45]
	ds_read_b128 v[232:235], v95 offset:17408
	ds_read_b128 v[86:89], v94 offset:53952
	s_waitcnt lgkmcnt(0)
	v_mfma_f32_16x16x32_bf16 v[42:45], v[86:89], v[60:63], v[42:45]
	s_nop 7
	v_cvt_pk_bf16_f32 v42, v42, v43
	v_cvt_pk_bf16_f32 v43, v44, v45
	global_store_dwordx2 v[32:33], v[42:43], off offset:64
	v_mfma_f32_16x16x32_bf16 v[34:37], v[236:239], v[216:219], 0
	ds_read_b128 v[216:219], v95 offset:17472
	ds_read_b128 v[236:239], v120 offset:64
	ds_read_b128 v[42:45], v95 offset:42816
	s_waitcnt lgkmcnt(0)
	v_mfma_f32_16x16x32_bf16 v[34:37], v[42:45], v[220:223], v[34:37]
	ds_read_b128 v[220:223], v95 offset:19712
	v_mfma_f32_16x16x32_bf16 v[34:37], v[244:247], v[48:51], v[34:37]
	ds_read_b128 v[244:247], v95 offset:19776
	v_mfma_f32_16x16x32_bf16 v[34:37], v[224:227], v[52:55], v[34:37]
	ds_read_b128 v[224:227], v120 offset:128
	v_mfma_f32_16x16x32_bf16 v[34:37], v[248:251], v[56:59], v[34:37]
	ds_read_b128 v[248:251], v95 offset:22016
	v_mfma_f32_16x16x32_bf16 v[34:37], v[252:255], v[60:63], v[34:37]
	ds_read_b128 v[252:255], v95 offset:22080
	s_nop 7
	v_cvt_pk_bf16_f32 v34, v34, v35
	v_cvt_pk_bf16_f32 v35, v36, v37
	global_store_dwordx2 v[32:33], v[34:35], off offset:96
	ds_read_b128 v[36:39], v46 offset:35840
	ds_read_b128 v[32:35], v46 offset:35904
	v_pk_mul_f32 v[12:13], v[12:13], v[228:229]
	v_pk_mul_f32 v[14:15], v[14:15], v[230:231]
	ds_read_b128 v[228:231], v120 offset:192
	s_waitcnt lgkmcnt(2)
	v_mfma_f32_16x16x32_bf16 v[12:15], v[232:235], v[36:39], v[12:15]
	ds_read_b128 v[232:235], v95 offset:24320
	s_waitcnt lgkmcnt(2)
	v_mfma_f32_16x16x32_bf16 v[12:15], v[216:219], v[32:35], v[12:15]
	ds_read_b128 v[216:219], v95 offset:24384
	v_pk_mul_f32 v[0:1], v[0:1], v[236:237]
	v_pk_mul_f32 v[2:3], v[2:3], v[238:239]
	ds_read_b128 v[236:239], v120 offset:256
	s_nop 0
	v_mfma_f32_16x16x32_bf16 v[0:3], v[220:223], v[36:39], v[0:3]
	ds_read_b128 v[220:223], v95 offset:26624
	v_mfma_f32_16x16x32_bf16 v[0:3], v[244:247], v[32:35], v[0:3]
	ds_read_b128 v[244:247], v95 offset:26688
	v_pk_mul_f32 v[8:9], v[8:9], v[224:225]
	v_pk_mul_f32 v[10:11], v[10:11], v[226:227]
	ds_read_b128 v[224:227], v120 offset:320
	s_nop 0
	v_mfma_f32_16x16x32_bf16 v[8:11], v[248:251], v[36:39], v[8:11]
	ds_read_b128 v[248:251], v95 offset:28928
	v_mfma_f32_16x16x32_bf16 v[8:11], v[252:255], v[32:35], v[8:11]
	ds_read_b128 v[252:255], v95 offset:28992
	s_waitcnt lgkmcnt(8)
	v_pk_mul_f32 v[4:5], v[4:5], v[228:229]
	v_pk_mul_f32 v[6:7], v[6:7], v[230:231]
	ds_read_b128 v[228:231], v120 offset:384
	s_waitcnt lgkmcnt(8)
	v_mfma_f32_16x16x32_bf16 v[4:7], v[232:235], v[36:39], v[4:7]
	ds_read_b128 v[232:235], v95 offset:31232
	s_waitcnt lgkmcnt(8)
	v_mfma_f32_16x16x32_bf16 v[4:7], v[216:219], v[32:35], v[4:7]
	ds_read_b128 v[216:219], v95 offset:31296
	s_waitcnt lgkmcnt(8)
	v_pk_mul_f32 v[20:21], v[20:21], v[236:237]
	v_pk_mul_f32 v[22:23], v[22:23], v[238:239]
	ds_read_b128 v[236:239], v120 offset:448
	s_waitcnt lgkmcnt(8)
	v_mfma_f32_16x16x32_bf16 v[20:23], v[220:223], v[36:39], v[20:23]
	s_waitcnt lgkmcnt(7)
	v_mfma_f32_16x16x32_bf16 v[20:23], v[244:247], v[32:35], v[20:23]
	s_waitcnt lgkmcnt(6)
	v_pk_mul_f32 v[16:17], v[16:17], v[224:225]
	v_pk_mul_f32 v[18:19], v[18:19], v[226:227]
	s_waitcnt lgkmcnt(5)
	s_nop 0
	v_mfma_f32_16x16x32_bf16 v[16:19], v[248:251], v[36:39], v[16:19]
	s_waitcnt lgkmcnt(4)
	v_mfma_f32_16x16x32_bf16 v[16:19], v[252:255], v[32:35], v[16:19]
	s_waitcnt lgkmcnt(3)
	v_pk_mul_f32 v[24:25], v[24:25], v[228:229]
	v_pk_mul_f32 v[26:27], v[26:27], v[230:231]
	s_waitcnt lgkmcnt(2)
	s_nop 0
	v_mfma_f32_16x16x32_bf16 v[24:27], v[232:235], v[36:39], v[24:27]
	s_waitcnt lgkmcnt(1)
	v_mfma_f32_16x16x32_bf16 v[24:27], v[216:219], v[32:35], v[24:27]
	s_waitcnt lgkmcnt(0)
	v_pk_mul_f32 v[28:29], v[28:29], v[236:237]
	v_pk_mul_f32 v[30:31], v[30:31], v[238:239]
	ds_read_b128 v[40:43], v95 offset:33536
	s_waitcnt lgkmcnt(0)
	v_mfma_f32_16x16x32_bf16 v[28:31], v[40:43], v[36:39], v[28:31]
	ds_read_b128 v[36:39], v95 offset:33600
	s_waitcnt lgkmcnt(0)
	s_barrier
	v_mfma_f32_16x16x32_bf16 v[28:31], v[36:39], v[32:35], v[28:31]
	s_andn2_b64 exec, exec, s[56:57]
	s_cbranch_execz .LBB0_1511
